# wave butterfly reductions in conv tail, samp_b, samp_hg via DPP + permlane swap instead of ds_bpermute (same pairing order, bit-identical sums)
# speedup vs baseline: 1.0038x; 1.0038x over previous
.LBB0_527:
	s_or_b64 exec, exec, s[0:1]
	global_load_dwordx4 v[0:3], v[48:49], off
	s_waitcnt lgkmcnt(0)
	s_barrier
	global_load_dwordx2 v[46:47], v[56:57], off
	global_load_dwordx2 v[132:133], v[58:59], off
	global_load_dwordx2 v[134:135], v[60:61], off
	global_load_dwordx2 v[136:137], v[62:63], off
	global_load_dwordx2 v[138:139], v[64:65], off
	global_load_dwordx2 v[140:141], v[66:67], off
	global_load_dwordx2 v[142:143], v[68:69], off
	global_load_dwordx2 v[144:145], v[70:71], off
	global_load_dwordx2 v[162:163], v[72:73], off
	global_load_dwordx2 v[164:165], v[74:75], off
	global_load_dwordx2 v[44:45], v[76:77], off
	global_load_dwordx2 v[42:43], v[78:79], off
	global_load_dwordx2 v[40:41], v[82:83], off
	global_load_dwordx2 v[38:39], v[84:85], off
	global_load_dwordx2 v[36:37], v[86:87], off
	global_load_dwordx2 v[34:35], v[88:89], off
	global_load_dwordx2 v[32:33], v[90:91], off
	global_load_dwordx2 v[30:31], v[92:93], off
	global_load_dwordx2 v[28:29], v[94:95], off
	global_load_dwordx2 v[26:27], v[96:97], off
	global_load_dwordx2 v[24:25], v[98:99], off
	global_load_dwordx2 v[22:23], v[100:101], off
	global_load_dwordx2 v[20:21], v[102:103], off
	global_load_dwordx2 v[18:19], v[104:105], off
	global_load_dwordx2 v[16:17], v[106:107], off
	global_load_dwordx2 v[14:15], v[108:109], off
	global_load_dwordx2 v[12:13], v[110:111], off
	global_load_dwordx2 v[10:11], v[112:113], off
	global_load_dwordx2 v[8:9], v[114:115], off
	global_load_dwordx2 v[4:5], v[116:117], off
	global_load_dwordx2 v[6:7], v[118:119], off
	ds_read2st64_b64 v[124:127], v148 offset1:2
	ds_read2st64_b64 v[128:131], v148 offset0:4 offset1:6
	s_waitcnt vmcnt(30) lgkmcnt(1)
	v_pk_fma_f32 v[124:125], v[46:47], v[124:125], v[0:1]
	v_pk_fma_f32 v[166:167], v[46:47], v[126:127], v[0:1]
	s_waitcnt vmcnt(29)
	v_pk_fma_f32 v[124:125], v[132:133], v[126:127], v[124:125]
	s_waitcnt lgkmcnt(0)
	v_pk_fma_f32 v[168:169], v[46:47], v[128:129], v[0:1]
	v_pk_fma_f32 v[166:167], v[132:133], v[128:129], v[166:167]
	s_waitcnt vmcnt(28)
	v_pk_fma_f32 v[128:129], v[134:135], v[128:129], v[124:125]
	ds_read2st64_b64 v[124:127], v148 offset0:8 offset1:10
	s_waitcnt vmcnt(27)
	v_pk_fma_f32 v[128:129], v[136:137], v[130:131], v[128:129]
	v_pk_fma_f32 v[166:167], v[134:135], v[130:131], v[166:167]
	v_pk_fma_f32 v[168:169], v[132:133], v[130:131], v[168:169]
	v_pk_fma_f32 v[130:131], v[46:47], v[130:131], v[0:1]
	s_waitcnt vmcnt(26) lgkmcnt(0)
	v_pk_fma_f32 v[128:129], v[138:139], v[124:125], v[128:129]
	v_pk_fma_f32 v[170:171], v[132:133], v[124:125], v[130:131]
	s_waitcnt vmcnt(25)
	v_pk_fma_f32 v[172:173], v[140:141], v[126:127], v[128:129]
	ds_read2st64_b64 v[128:131], v148 offset0:12 offset1:14
	v_pk_fma_f32 v[166:167], v[136:137], v[124:125], v[166:167]
	v_pk_fma_f32 v[168:169], v[134:135], v[124:125], v[168:169]
	v_pk_fma_f32 v[124:125], v[46:47], v[124:125], v[0:1]
	v_pk_fma_f32 v[166:167], v[138:139], v[126:127], v[166:167]
	v_pk_fma_f32 v[168:169], v[136:137], v[126:127], v[168:169]
	v_pk_fma_f32 v[170:171], v[134:135], v[126:127], v[170:171]
	v_pk_fma_f32 v[124:125], v[132:133], v[126:127], v[124:125]
	v_pk_fma_f32 v[126:127], v[46:47], v[126:127], v[0:1]
	s_waitcnt vmcnt(24) lgkmcnt(0)
	v_pk_fma_f32 v[172:173], v[142:143], v[128:129], v[172:173]
	v_pk_fma_f32 v[166:167], v[140:141], v[128:129], v[166:167]
	v_pk_fma_f32 v[168:169], v[138:139], v[128:129], v[168:169]
	v_pk_fma_f32 v[170:171], v[136:137], v[128:129], v[170:171]
	v_pk_fma_f32 v[124:125], v[134:135], v[128:129], v[124:125]
	v_pk_fma_f32 v[126:127], v[132:133], v[128:129], v[126:127]
	v_pk_fma_f32 v[128:129], v[46:47], v[128:129], v[0:1]
	s_waitcnt vmcnt(23)
	v_pk_fma_f32 v[172:173], v[144:145], v[130:131], v[172:173]
	v_pk_fma_f32 v[166:167], v[142:143], v[130:131], v[166:167]
	v_pk_fma_f32 v[168:169], v[140:141], v[130:131], v[168:169]
	v_pk_fma_f32 v[170:171], v[138:139], v[130:131], v[170:171]
	v_pk_fma_f32 v[174:175], v[136:137], v[130:131], v[124:125]
	v_pk_fma_f32 v[176:177], v[134:135], v[130:131], v[126:127]
	v_pk_fma_f32 v[128:129], v[132:133], v[130:131], v[128:129]
	v_pk_fma_f32 v[0:1], v[46:47], v[130:131], v[0:1]
	ds_read2st64_b64 v[124:127], v148 offset0:16 offset1:18
	s_waitcnt vmcnt(22) lgkmcnt(0)
	v_pk_fma_f32 v[46:47], v[162:163], v[124:125], v[172:173]
	v_pk_fma_f32 v[130:131], v[144:145], v[124:125], v[166:167]
	v_pk_fma_f32 v[166:167], v[142:143], v[124:125], v[168:169]
	v_pk_fma_f32 v[168:169], v[140:141], v[124:125], v[170:171]
	v_pk_fma_f32 v[170:171], v[138:139], v[124:125], v[174:175]
	v_pk_fma_f32 v[172:173], v[136:137], v[124:125], v[176:177]
	v_pk_fma_f32 v[128:129], v[134:135], v[124:125], v[128:129]
	v_pk_fma_f32 v[0:1], v[132:133], v[124:125], v[0:1]
	s_waitcnt vmcnt(21)
	v_pk_fma_f32 v[46:47], v[164:165], v[126:127], v[46:47]
	v_pk_fma_f32 v[130:131], v[162:163], v[126:127], v[130:131]
	v_pk_fma_f32 v[132:133], v[144:145], v[126:127], v[166:167]
	v_pk_fma_f32 v[166:167], v[142:143], v[126:127], v[168:169]
	v_pk_fma_f32 v[168:169], v[140:141], v[126:127], v[170:171]
	v_pk_fma_f32 v[170:171], v[138:139], v[126:127], v[172:173]
	v_pk_fma_f32 v[128:129], v[136:137], v[126:127], v[128:129]
	v_pk_fma_f32 v[0:1], v[134:135], v[126:127], v[0:1]
	ds_read2st64_b64 v[124:127], v148 offset0:20 offset1:22
	s_waitcnt vmcnt(20) lgkmcnt(0)
	v_pk_fma_f32 v[46:47], v[44:45], v[124:125], v[46:47]
	v_pk_fma_f32 v[130:131], v[164:165], v[124:125], v[130:131]
	v_pk_fma_f32 v[132:133], v[162:163], v[124:125], v[132:133]
	v_pk_fma_f32 v[134:135], v[144:145], v[124:125], v[166:167]
	v_pk_fma_f32 v[166:167], v[142:143], v[124:125], v[168:169]
	v_pk_fma_f32 v[168:169], v[140:141], v[124:125], v[170:171]
	v_pk_fma_f32 v[128:129], v[138:139], v[124:125], v[128:129]
	v_pk_fma_f32 v[0:1], v[136:137], v[124:125], v[0:1]
	s_waitcnt vmcnt(19)
	v_pk_fma_f32 v[46:47], v[42:43], v[126:127], v[46:47]
	v_pk_fma_f32 v[130:131], v[44:45], v[126:127], v[130:131]
	v_pk_fma_f32 v[132:133], v[164:165], v[126:127], v[132:133]
	v_pk_fma_f32 v[134:135], v[162:163], v[126:127], v[134:135]
	v_pk_fma_f32 v[136:137], v[144:145], v[126:127], v[166:167]
	v_pk_fma_f32 v[166:167], v[142:143], v[126:127], v[168:169]
	v_pk_fma_f32 v[128:129], v[140:141], v[126:127], v[128:129]
	v_pk_fma_f32 v[0:1], v[138:139], v[126:127], v[0:1]
	ds_read2st64_b64 v[124:127], v148 offset0:24 offset1:26
	s_waitcnt vmcnt(18) lgkmcnt(0)
	v_pk_fma_f32 v[46:47], v[40:41], v[124:125], v[46:47]
	v_pk_fma_f32 v[130:131], v[42:43], v[124:125], v[130:131]
	v_pk_fma_f32 v[132:133], v[44:45], v[124:125], v[132:133]
	v_pk_fma_f32 v[134:135], v[164:165], v[124:125], v[134:135]
	v_pk_fma_f32 v[136:137], v[162:163], v[124:125], v[136:137]
	v_pk_fma_f32 v[138:139], v[144:145], v[124:125], v[166:167]
	v_pk_fma_f32 v[128:129], v[142:143], v[124:125], v[128:129]
	v_pk_fma_f32 v[0:1], v[140:141], v[124:125], v[0:1]
	s_waitcnt vmcnt(17)
	v_pk_fma_f32 v[46:47], v[38:39], v[126:127], v[46:47]
	v_pk_fma_f32 v[130:131], v[40:41], v[126:127], v[130:131]
	v_pk_fma_f32 v[132:133], v[42:43], v[126:127], v[132:133]
	v_pk_fma_f32 v[134:135], v[44:45], v[126:127], v[134:135]
	v_pk_fma_f32 v[136:137], v[164:165], v[126:127], v[136:137]
	v_pk_fma_f32 v[138:139], v[162:163], v[126:127], v[138:139]
	v_pk_fma_f32 v[128:129], v[144:145], v[126:127], v[128:129]
	v_pk_fma_f32 v[0:1], v[142:143], v[126:127], v[0:1]
	ds_read2st64_b64 v[124:127], v148 offset0:28 offset1:30
	s_waitcnt vmcnt(16) lgkmcnt(0)
	v_pk_fma_f32 v[46:47], v[36:37], v[124:125], v[46:47]
	v_pk_fma_f32 v[130:131], v[38:39], v[124:125], v[130:131]
	v_pk_fma_f32 v[132:133], v[40:41], v[124:125], v[132:133]
	v_pk_fma_f32 v[134:135], v[42:43], v[124:125], v[134:135]
	v_pk_fma_f32 v[136:137], v[44:45], v[124:125], v[136:137]
	v_pk_fma_f32 v[138:139], v[164:165], v[124:125], v[138:139]
	v_pk_fma_f32 v[128:129], v[162:163], v[124:125], v[128:129]
	v_pk_fma_f32 v[0:1], v[144:145], v[124:125], v[0:1]
	s_waitcnt vmcnt(15)
	v_pk_fma_f32 v[46:47], v[34:35], v[126:127], v[46:47]
	v_pk_fma_f32 v[130:131], v[36:37], v[126:127], v[130:131]
	v_pk_fma_f32 v[132:133], v[38:39], v[126:127], v[132:133]
	v_pk_fma_f32 v[134:135], v[40:41], v[126:127], v[134:135]
	v_pk_fma_f32 v[136:137], v[42:43], v[126:127], v[136:137]
	v_pk_fma_f32 v[138:139], v[44:45], v[126:127], v[138:139]
	v_pk_fma_f32 v[128:129], v[164:165], v[126:127], v[128:129]
	v_pk_fma_f32 v[0:1], v[162:163], v[126:127], v[0:1]
	ds_read2st64_b64 v[124:127], v148 offset0:32 offset1:34
	s_waitcnt vmcnt(14) lgkmcnt(0)
	v_pk_fma_f32 v[46:47], v[32:33], v[124:125], v[46:47]
	v_pk_fma_f32 v[0:1], v[164:165], v[124:125], v[0:1]
	v_pk_fma_f32 v[130:131], v[34:35], v[124:125], v[130:131]
	v_pk_fma_f32 v[132:133], v[36:37], v[124:125], v[132:133]
	v_pk_fma_f32 v[134:135], v[38:39], v[124:125], v[134:135]
	v_pk_fma_f32 v[136:137], v[40:41], v[124:125], v[136:137]
	v_pk_fma_f32 v[138:139], v[42:43], v[124:125], v[138:139]
	v_pk_fma_f32 v[128:129], v[44:45], v[124:125], v[128:129]
	s_waitcnt vmcnt(13)
	v_pk_fma_f32 v[124:125], v[30:31], v[126:127], v[46:47]
	v_pk_fma_f32 v[0:1], v[44:45], v[126:127], v[0:1]
	ds_read2st64_b64 v[44:47], v148 offset0:36 offset1:38
	v_pk_fma_f32 v[128:129], v[42:43], v[126:127], v[128:129]
	v_pk_fma_f32 v[138:139], v[40:41], v[126:127], v[138:139]
	v_pk_fma_f32 v[130:131], v[32:33], v[126:127], v[130:131]
	v_pk_fma_f32 v[132:133], v[34:35], v[126:127], v[132:133]
	s_waitcnt lgkmcnt(0)
	v_pk_fma_f32 v[0:1], v[42:43], v[44:45], v[0:1]
	v_pk_fma_f32 v[128:129], v[40:41], v[44:45], v[128:129]
	v_pk_fma_f32 v[0:1], v[40:41], v[46:47], v[0:1]
	ds_read2st64_b64 v[40:43], v148 offset0:40 offset1:42
	v_pk_fma_f32 v[134:135], v[36:37], v[126:127], v[134:135]
	v_pk_fma_f32 v[136:137], v[38:39], v[126:127], v[136:137]
	s_waitcnt vmcnt(12)
	v_pk_fma_f32 v[124:125], v[28:29], v[44:45], v[124:125]
	v_pk_fma_f32 v[126:127], v[30:31], v[44:45], v[130:131]
	v_pk_fma_f32 v[130:131], v[32:33], v[44:45], v[132:133]
	v_pk_fma_f32 v[132:133], v[34:35], v[44:45], v[134:135]
	v_pk_fma_f32 v[134:135], v[36:37], v[44:45], v[136:137]
	v_pk_fma_f32 v[136:137], v[38:39], v[44:45], v[138:139]
	v_pk_fma_f32 v[128:129], v[38:39], v[46:47], v[128:129]
	s_waitcnt lgkmcnt(0)
	v_pk_fma_f32 v[0:1], v[38:39], v[40:41], v[0:1]
	s_waitcnt vmcnt(11)
	v_pk_fma_f32 v[44:45], v[26:27], v[46:47], v[124:125]
	v_pk_fma_f32 v[124:125], v[28:29], v[46:47], v[126:127]
	v_pk_fma_f32 v[126:127], v[30:31], v[46:47], v[130:131]
	v_pk_fma_f32 v[130:131], v[32:33], v[46:47], v[132:133]
	v_pk_fma_f32 v[132:133], v[34:35], v[46:47], v[134:135]
	v_pk_fma_f32 v[134:135], v[36:37], v[46:47], v[136:137]
	v_pk_fma_f32 v[128:129], v[36:37], v[40:41], v[128:129]
	v_pk_fma_f32 v[0:1], v[36:37], v[42:43], v[0:1]
	ds_read2st64_b64 v[36:39], v148 offset0:44 offset1:46
	s_waitcnt vmcnt(10)
	v_pk_fma_f32 v[44:45], v[24:25], v[40:41], v[44:45]
	v_pk_fma_f32 v[46:47], v[26:27], v[40:41], v[124:125]
	v_pk_fma_f32 v[124:125], v[28:29], v[40:41], v[126:127]
	v_pk_fma_f32 v[126:127], v[30:31], v[40:41], v[130:131]
	v_pk_fma_f32 v[130:131], v[32:33], v[40:41], v[132:133]
	v_pk_fma_f32 v[132:133], v[34:35], v[40:41], v[134:135]
	s_waitcnt vmcnt(9)
	v_pk_fma_f32 v[40:41], v[22:23], v[42:43], v[44:45]
	v_pk_fma_f32 v[44:45], v[24:25], v[42:43], v[46:47]
	v_pk_fma_f32 v[46:47], v[26:27], v[42:43], v[124:125]
	v_pk_fma_f32 v[124:125], v[28:29], v[42:43], v[126:127]
	v_pk_fma_f32 v[126:127], v[30:31], v[42:43], v[130:131]
	v_pk_fma_f32 v[130:131], v[32:33], v[42:43], v[132:133]
	v_pk_fma_f32 v[128:129], v[34:35], v[42:43], v[128:129]
	s_waitcnt vmcnt(8) lgkmcnt(0)
	v_pk_fma_f32 v[40:41], v[20:21], v[36:37], v[40:41]
	v_pk_fma_f32 v[42:43], v[22:23], v[36:37], v[44:45]
	v_pk_fma_f32 v[44:45], v[24:25], v[36:37], v[46:47]
	v_pk_fma_f32 v[46:47], v[26:27], v[36:37], v[124:125]
	v_pk_fma_f32 v[124:125], v[28:29], v[36:37], v[126:127]
	v_pk_fma_f32 v[126:127], v[30:31], v[36:37], v[130:131]
	v_pk_fma_f32 v[128:129], v[32:33], v[36:37], v[128:129]
	v_pk_fma_f32 v[0:1], v[34:35], v[36:37], v[0:1]
	s_waitcnt vmcnt(7)
	v_pk_fma_f32 v[36:37], v[18:19], v[38:39], v[40:41]
	v_pk_fma_f32 v[40:41], v[20:21], v[38:39], v[42:43]
	v_pk_fma_f32 v[42:43], v[22:23], v[38:39], v[44:45]
	v_pk_fma_f32 v[44:45], v[24:25], v[38:39], v[46:47]
	v_pk_fma_f32 v[46:47], v[26:27], v[38:39], v[124:125]
	v_pk_fma_f32 v[124:125], v[28:29], v[38:39], v[126:127]
	v_pk_fma_f32 v[126:127], v[30:31], v[38:39], v[128:129]
	v_pk_fma_f32 v[0:1], v[32:33], v[38:39], v[0:1]
	ds_read2st64_b64 v[32:35], v148 offset0:48 offset1:50
	s_waitcnt lgkmcnt(0)
	v_pk_fma_f32 v[0:1], v[30:31], v[32:33], v[0:1]
	v_pk_fma_f32 v[38:39], v[18:19], v[32:33], v[40:41]
	v_pk_fma_f32 v[40:41], v[20:21], v[32:33], v[42:43]
	v_pk_fma_f32 v[42:43], v[22:23], v[32:33], v[44:45]
	v_pk_fma_f32 v[44:45], v[24:25], v[32:33], v[46:47]
	v_pk_fma_f32 v[46:47], v[26:27], v[32:33], v[124:125]
	v_pk_fma_f32 v[124:125], v[28:29], v[32:33], v[126:127]
	v_pk_fma_f32 v[0:1], v[28:29], v[34:35], v[0:1]
	ds_read2st64_b64 v[28:31], v148 offset0:52 offset1:54
	s_waitcnt vmcnt(6)
	v_pk_fma_f32 v[36:37], v[16:17], v[32:33], v[36:37]
	s_waitcnt lgkmcnt(0)
	v_pk_fma_f32 v[0:1], v[26:27], v[28:29], v[0:1]
	s_waitcnt vmcnt(5)
	v_pk_fma_f32 v[32:33], v[14:15], v[34:35], v[36:37]
	v_pk_fma_f32 v[36:37], v[16:17], v[34:35], v[38:39]
	v_pk_fma_f32 v[38:39], v[18:19], v[34:35], v[40:41]
	v_pk_fma_f32 v[40:41], v[20:21], v[34:35], v[42:43]
	v_pk_fma_f32 v[42:43], v[22:23], v[34:35], v[44:45]
	v_pk_fma_f32 v[44:45], v[24:25], v[34:35], v[46:47]
	v_pk_fma_f32 v[46:47], v[26:27], v[34:35], v[124:125]
	v_pk_fma_f32 v[34:35], v[14:15], v[28:29], v[36:37]
	v_pk_fma_f32 v[36:37], v[16:17], v[28:29], v[38:39]
	v_pk_fma_f32 v[38:39], v[18:19], v[28:29], v[40:41]
	v_pk_fma_f32 v[40:41], v[20:21], v[28:29], v[42:43]
	v_pk_fma_f32 v[42:43], v[22:23], v[28:29], v[44:45]
	v_pk_fma_f32 v[44:45], v[24:25], v[28:29], v[46:47]
	v_pk_fma_f32 v[0:1], v[24:25], v[30:31], v[0:1]
	ds_read2st64_b64 v[24:27], v148 offset0:56 offset1:58
	s_waitcnt vmcnt(4)
	v_pk_fma_f32 v[32:33], v[12:13], v[28:29], v[32:33]
	s_waitcnt lgkmcnt(0)
	v_pk_fma_f32 v[0:1], v[22:23], v[24:25], v[0:1]
	s_waitcnt vmcnt(3)
	v_pk_fma_f32 v[28:29], v[10:11], v[30:31], v[32:33]
	v_pk_fma_f32 v[32:33], v[12:13], v[30:31], v[34:35]
	v_pk_fma_f32 v[34:35], v[14:15], v[30:31], v[36:37]
	v_pk_fma_f32 v[36:37], v[16:17], v[30:31], v[38:39]
	v_pk_fma_f32 v[38:39], v[18:19], v[30:31], v[40:41]
	v_pk_fma_f32 v[40:41], v[20:21], v[30:31], v[42:43]
	v_pk_fma_f32 v[42:43], v[22:23], v[30:31], v[44:45]
	v_pk_fma_f32 v[30:31], v[10:11], v[24:25], v[32:33]
	v_pk_fma_f32 v[32:33], v[12:13], v[24:25], v[34:35]
	v_pk_fma_f32 v[34:35], v[14:15], v[24:25], v[36:37]
	v_pk_fma_f32 v[36:37], v[16:17], v[24:25], v[38:39]
	v_pk_fma_f32 v[38:39], v[18:19], v[24:25], v[40:41]
	v_pk_fma_f32 v[40:41], v[20:21], v[24:25], v[42:43]
	v_pk_fma_f32 v[0:1], v[20:21], v[26:27], v[0:1]
	ds_read2st64_b64 v[20:23], v148 offset0:60 offset1:62
	s_waitcnt vmcnt(2)
	v_pk_fma_f32 v[28:29], v[8:9], v[24:25], v[28:29]
	s_waitcnt lgkmcnt(0)
	v_pk_fma_f32 v[0:1], v[18:19], v[20:21], v[0:1]
	s_waitcnt vmcnt(1)
	v_pk_fma_f32 v[24:25], v[4:5], v[26:27], v[28:29]
	v_pk_fma_f32 v[28:29], v[8:9], v[26:27], v[30:31]
	v_pk_fma_f32 v[30:31], v[10:11], v[26:27], v[32:33]
	v_pk_fma_f32 v[32:33], v[12:13], v[26:27], v[34:35]
	v_pk_fma_f32 v[34:35], v[14:15], v[26:27], v[36:37]
	v_pk_fma_f32 v[36:37], v[16:17], v[26:27], v[38:39]
	v_pk_fma_f32 v[38:39], v[18:19], v[26:27], v[40:41]
	s_waitcnt vmcnt(0)
	v_pk_fma_f32 v[128:129], v[6:7], v[20:21], v[24:25]
	v_pk_fma_f32 v[24:25], v[4:5], v[20:21], v[28:29]
	v_pk_fma_f32 v[26:27], v[8:9], v[20:21], v[30:31]
	v_pk_fma_f32 v[28:29], v[10:11], v[20:21], v[32:33]
	v_pk_fma_f32 v[30:31], v[12:13], v[20:21], v[34:35]
	v_pk_fma_f32 v[32:33], v[14:15], v[20:21], v[36:37]
	v_pk_fma_f32 v[34:35], v[16:17], v[20:21], v[38:39]
	v_pk_fma_f32 v[44:45], v[6:7], v[22:23], v[24:25]
	v_pk_fma_f32 v[20:21], v[4:5], v[22:23], v[26:27]
	v_pk_fma_f32 v[24:25], v[8:9], v[22:23], v[28:29]
	v_pk_fma_f32 v[26:27], v[10:11], v[22:23], v[30:31]
	v_pk_fma_f32 v[28:29], v[12:13], v[22:23], v[32:33]
	v_pk_fma_f32 v[30:31], v[14:15], v[22:23], v[34:35]
	v_pk_fma_f32 v[0:1], v[16:17], v[22:23], v[0:1]
	ds_read2st64_b64 v[16:19], v148 offset0:64 offset1:66
	s_waitcnt lgkmcnt(0)
	v_pk_fma_f32 v[0:1], v[14:15], v[16:17], v[0:1]
	v_pk_fma_f32 v[22:23], v[8:9], v[16:17], v[26:27]
	v_pk_fma_f32 v[26:27], v[12:13], v[16:17], v[30:31]
	v_pk_fma_f32 v[0:1], v[12:13], v[18:19], v[0:1]
	ds_read2st64_b64 v[12:15], v148 offset0:68 offset1:70
	v_pk_fma_f32 v[36:37], v[6:7], v[16:17], v[20:21]
	v_pk_fma_f32 v[20:21], v[4:5], v[16:17], v[24:25]
	v_pk_fma_f32 v[24:25], v[10:11], v[16:17], v[28:29]
	v_pk_fma_f32 v[16:17], v[4:5], v[18:19], v[22:23]
	v_pk_fma_f32 v[22:23], v[8:9], v[18:19], v[24:25]
	v_pk_fma_f32 v[24:25], v[10:11], v[18:19], v[26:27]
	v_pk_fma_f32 v[28:29], v[6:7], v[18:19], v[20:21]
	s_waitcnt lgkmcnt(0)
	v_pk_fma_f32 v[20:21], v[6:7], v[12:13], v[16:17]
	v_pk_fma_f32 v[16:17], v[4:5], v[12:13], v[22:23]
	v_pk_fma_f32 v[18:19], v[8:9], v[12:13], v[24:25]
	v_pk_fma_f32 v[0:1], v[10:11], v[12:13], v[0:1]
	v_pk_fma_f32 v[12:13], v[6:7], v[14:15], v[16:17]
	v_pk_fma_f32 v[10:11], v[4:5], v[14:15], v[18:19]
	v_pk_fma_f32 v[0:1], v[8:9], v[14:15], v[0:1]
	ds_read2st64_b64 v[14:17], v148 offset0:72 offset1:74
	s_waitcnt lgkmcnt(0)
	v_pk_fma_f32 v[0:1], v[4:5], v[14:15], v[0:1]
	v_pk_fma_f32 v[10:11], v[6:7], v[14:15], v[10:11]
	v_pk_fma_f32 v[8:9], v[6:7], v[16:17], v[0:1]
	global_load_dwordx2 v[144:145], v[56:57], off offset:8
	global_load_dwordx2 v[166:167], v[58:59], off offset:8
	global_load_dwordx2 v[168:169], v[60:61], off offset:8
	global_load_dwordx2 v[170:171], v[62:63], off offset:8
	global_load_dwordx2 v[172:173], v[64:65], off offset:8
	global_load_dwordx2 v[174:175], v[66:67], off offset:8
	global_load_dwordx2 v[176:177], v[68:69], off offset:8
	global_load_dwordx2 v[178:179], v[70:71], off offset:8
	global_load_dwordx2 v[180:181], v[72:73], off offset:8
	global_load_dwordx2 v[136:137], v[74:75], off offset:8
	global_load_dwordx2 v[134:135], v[76:77], off offset:8
	global_load_dwordx2 v[132:133], v[78:79], off offset:8
	global_load_dwordx2 v[130:131], v[82:83], off offset:8
	global_load_dwordx2 v[126:127], v[84:85], off offset:8
	global_load_dwordx2 v[124:125], v[86:87], off offset:8
	global_load_dwordx2 v[46:47], v[88:89], off offset:8
	global_load_dwordx2 v[42:43], v[90:91], off offset:8
	global_load_dwordx2 v[40:41], v[92:93], off offset:8
	global_load_dwordx2 v[38:39], v[94:95], off offset:8
	global_load_dwordx2 v[34:35], v[96:97], off offset:8
	global_load_dwordx2 v[32:33], v[98:99], off offset:8
	global_load_dwordx2 v[30:31], v[100:101], off offset:8
	global_load_dwordx2 v[26:27], v[102:103], off offset:8
	global_load_dwordx2 v[24:25], v[104:105], off offset:8
	global_load_dwordx2 v[22:23], v[106:107], off offset:8
	global_load_dwordx2 v[18:19], v[108:109], off offset:8
	global_load_dwordx2 v[16:17], v[110:111], off offset:8
	global_load_dwordx2 v[14:15], v[112:113], off offset:8
	global_load_dwordx2 v[6:7], v[114:115], off offset:8
	global_load_dwordx2 v[0:1], v[116:117], off offset:8
	global_load_dwordx2 v[4:5], v[118:119], off offset:8
	ds_read2_b64 v[140:143], v148 offset0:1 offset1:129
	v_add_u32_e32 v138, 8, v148
	ds_read2st64_b64 v[162:165], v138 offset0:4 offset1:6
	s_waitcnt vmcnt(30) lgkmcnt(1)
	v_pk_fma_f32 v[140:141], v[144:145], v[140:141], v[2:3]
	s_waitcnt vmcnt(29)
	v_pk_fma_f32 v[140:141], v[166:167], v[142:143], v[140:141]
	v_pk_fma_f32 v[182:183], v[144:145], v[142:143], v[2:3]
	s_waitcnt vmcnt(28) lgkmcnt(0)
	v_pk_fma_f32 v[184:185], v[168:169], v[162:163], v[140:141]
	ds_read2st64_b64 v[140:143], v138 offset0:8 offset1:10
	v_pk_fma_f32 v[182:183], v[166:167], v[162:163], v[182:183]
	v_pk_fma_f32 v[162:163], v[144:145], v[162:163], v[2:3]
	s_waitcnt vmcnt(27)
	v_pk_fma_f32 v[184:185], v[170:171], v[164:165], v[184:185]
	v_pk_fma_f32 v[182:183], v[168:169], v[164:165], v[182:183]
	v_pk_fma_f32 v[162:163], v[166:167], v[164:165], v[162:163]
	v_pk_fma_f32 v[164:165], v[144:145], v[164:165], v[2:3]
	s_waitcnt lgkmcnt(0)
	v_pk_fma_f32 v[186:187], v[168:169], v[140:141], v[162:163]
	v_pk_fma_f32 v[188:189], v[166:167], v[140:141], v[164:165]
	ds_read2st64_b64 v[162:165], v138 offset0:12 offset1:14
	s_waitcnt vmcnt(26)
	v_pk_fma_f32 v[184:185], v[172:173], v[140:141], v[184:185]
	v_pk_fma_f32 v[182:183], v[170:171], v[140:141], v[182:183]
	v_pk_fma_f32 v[140:141], v[144:145], v[140:141], v[2:3]
	s_waitcnt vmcnt(25)
	v_pk_fma_f32 v[184:185], v[174:175], v[142:143], v[184:185]
	v_pk_fma_f32 v[182:183], v[172:173], v[142:143], v[182:183]
	v_pk_fma_f32 v[186:187], v[170:171], v[142:143], v[186:187]
	v_pk_fma_f32 v[188:189], v[168:169], v[142:143], v[188:189]
	v_pk_fma_f32 v[140:141], v[166:167], v[142:143], v[140:141]
	v_pk_fma_f32 v[142:143], v[144:145], v[142:143], v[2:3]
	s_waitcnt vmcnt(24) lgkmcnt(0)
	v_pk_fma_f32 v[184:185], v[176:177], v[162:163], v[184:185]
	v_pk_fma_f32 v[182:183], v[174:175], v[162:163], v[182:183]
	v_pk_fma_f32 v[186:187], v[172:173], v[162:163], v[186:187]
	v_pk_fma_f32 v[188:189], v[170:171], v[162:163], v[188:189]
	v_pk_fma_f32 v[140:141], v[168:169], v[162:163], v[140:141]
	v_pk_fma_f32 v[142:143], v[166:167], v[162:163], v[142:143]
	v_pk_fma_f32 v[162:163], v[144:145], v[162:163], v[2:3]
	s_waitcnt vmcnt(23)
	v_pk_fma_f32 v[184:185], v[178:179], v[164:165], v[184:185]
	v_pk_fma_f32 v[182:183], v[176:177], v[164:165], v[182:183]
	v_pk_fma_f32 v[186:187], v[174:175], v[164:165], v[186:187]
	v_pk_fma_f32 v[188:189], v[172:173], v[164:165], v[188:189]
	v_pk_fma_f32 v[190:191], v[170:171], v[164:165], v[140:141]
	v_pk_fma_f32 v[192:193], v[168:169], v[164:165], v[142:143]
	v_pk_fma_f32 v[162:163], v[166:167], v[164:165], v[162:163]
	v_pk_fma_f32 v[2:3], v[144:145], v[164:165], v[2:3]
	ds_read2st64_b64 v[140:143], v138 offset0:16 offset1:18
	s_waitcnt vmcnt(22) lgkmcnt(0)
	v_pk_fma_f32 v[144:145], v[180:181], v[140:141], v[184:185]
	v_pk_fma_f32 v[164:165], v[178:179], v[140:141], v[182:183]
	v_pk_fma_f32 v[182:183], v[176:177], v[140:141], v[186:187]
	v_pk_fma_f32 v[184:185], v[174:175], v[140:141], v[188:189]
	v_pk_fma_f32 v[186:187], v[172:173], v[140:141], v[190:191]
	v_pk_fma_f32 v[188:189], v[170:171], v[140:141], v[192:193]
	v_pk_fma_f32 v[162:163], v[168:169], v[140:141], v[162:163]
	v_pk_fma_f32 v[2:3], v[166:167], v[140:141], v[2:3]
	s_waitcnt vmcnt(21)
	v_pk_fma_f32 v[144:145], v[136:137], v[142:143], v[144:145]
	v_pk_fma_f32 v[164:165], v[180:181], v[142:143], v[164:165]
	v_pk_fma_f32 v[166:167], v[178:179], v[142:143], v[182:183]
	v_pk_fma_f32 v[182:183], v[176:177], v[142:143], v[184:185]
	v_pk_fma_f32 v[184:185], v[174:175], v[142:143], v[186:187]
	v_pk_fma_f32 v[186:187], v[172:173], v[142:143], v[188:189]
	v_pk_fma_f32 v[162:163], v[170:171], v[142:143], v[162:163]
	v_pk_fma_f32 v[2:3], v[168:169], v[142:143], v[2:3]
	ds_read2st64_b64 v[140:143], v138 offset0:20 offset1:22
	s_waitcnt vmcnt(20) lgkmcnt(0)
	v_pk_fma_f32 v[144:145], v[134:135], v[140:141], v[144:145]
	v_pk_fma_f32 v[164:165], v[136:137], v[140:141], v[164:165]
	v_pk_fma_f32 v[166:167], v[180:181], v[140:141], v[166:167]
	v_pk_fma_f32 v[168:169], v[178:179], v[140:141], v[182:183]
	v_pk_fma_f32 v[182:183], v[176:177], v[140:141], v[184:185]
	v_pk_fma_f32 v[184:185], v[174:175], v[140:141], v[186:187]
	v_pk_fma_f32 v[162:163], v[172:173], v[140:141], v[162:163]
	v_pk_fma_f32 v[2:3], v[170:171], v[140:141], v[2:3]
	s_waitcnt vmcnt(19)
	v_pk_fma_f32 v[144:145], v[132:133], v[142:143], v[144:145]
	v_pk_fma_f32 v[164:165], v[134:135], v[142:143], v[164:165]
	v_pk_fma_f32 v[166:167], v[136:137], v[142:143], v[166:167]
	v_pk_fma_f32 v[168:169], v[180:181], v[142:143], v[168:169]
	v_pk_fma_f32 v[170:171], v[178:179], v[142:143], v[182:183]
	v_pk_fma_f32 v[182:183], v[176:177], v[142:143], v[184:185]
	v_pk_fma_f32 v[162:163], v[174:175], v[142:143], v[162:163]
	v_pk_fma_f32 v[2:3], v[172:173], v[142:143], v[2:3]
	ds_read2st64_b64 v[140:143], v138 offset0:24 offset1:26
	s_waitcnt vmcnt(18) lgkmcnt(0)
	v_pk_fma_f32 v[144:145], v[130:131], v[140:141], v[144:145]
	v_pk_fma_f32 v[164:165], v[132:133], v[140:141], v[164:165]
	v_pk_fma_f32 v[166:167], v[134:135], v[140:141], v[166:167]
	v_pk_fma_f32 v[168:169], v[136:137], v[140:141], v[168:169]
	v_pk_fma_f32 v[170:171], v[180:181], v[140:141], v[170:171]
	v_pk_fma_f32 v[172:173], v[178:179], v[140:141], v[182:183]
	v_pk_fma_f32 v[162:163], v[176:177], v[140:141], v[162:163]
	v_pk_fma_f32 v[2:3], v[174:175], v[140:141], v[2:3]
	s_waitcnt vmcnt(17)
	v_pk_fma_f32 v[144:145], v[126:127], v[142:143], v[144:145]
	v_pk_fma_f32 v[164:165], v[130:131], v[142:143], v[164:165]
	v_pk_fma_f32 v[166:167], v[132:133], v[142:143], v[166:167]
	v_pk_fma_f32 v[168:169], v[134:135], v[142:143], v[168:169]
	v_pk_fma_f32 v[170:171], v[136:137], v[142:143], v[170:171]
	v_pk_fma_f32 v[172:173], v[180:181], v[142:143], v[172:173]
	v_pk_fma_f32 v[162:163], v[178:179], v[142:143], v[162:163]
	v_pk_fma_f32 v[2:3], v[176:177], v[142:143], v[2:3]
	ds_read2st64_b64 v[140:143], v138 offset0:28 offset1:30
	s_waitcnt vmcnt(16) lgkmcnt(0)
	v_pk_fma_f32 v[144:145], v[124:125], v[140:141], v[144:145]
	v_pk_fma_f32 v[164:165], v[126:127], v[140:141], v[164:165]
	v_pk_fma_f32 v[166:167], v[130:131], v[140:141], v[166:167]
	v_pk_fma_f32 v[168:169], v[132:133], v[140:141], v[168:169]
	v_pk_fma_f32 v[170:171], v[134:135], v[140:141], v[170:171]
	v_pk_fma_f32 v[172:173], v[136:137], v[140:141], v[172:173]
	v_pk_fma_f32 v[162:163], v[180:181], v[140:141], v[162:163]
	v_pk_fma_f32 v[2:3], v[178:179], v[140:141], v[2:3]
	s_waitcnt vmcnt(15)
	v_pk_fma_f32 v[144:145], v[46:47], v[142:143], v[144:145]
	v_pk_fma_f32 v[164:165], v[124:125], v[142:143], v[164:165]
	v_pk_fma_f32 v[166:167], v[126:127], v[142:143], v[166:167]
	v_pk_fma_f32 v[168:169], v[130:131], v[142:143], v[168:169]
	v_pk_fma_f32 v[170:171], v[132:133], v[142:143], v[170:171]
	v_pk_fma_f32 v[172:173], v[134:135], v[142:143], v[172:173]
	v_pk_fma_f32 v[162:163], v[136:137], v[142:143], v[162:163]
	v_pk_fma_f32 v[2:3], v[180:181], v[142:143], v[2:3]
	ds_read2st64_b64 v[140:143], v138 offset0:32 offset1:34
	s_waitcnt lgkmcnt(0)
	v_pk_fma_f32 v[2:3], v[136:137], v[140:141], v[2:3]
	v_pk_fma_f32 v[162:163], v[134:135], v[140:141], v[162:163]
	v_pk_fma_f32 v[2:3], v[134:135], v[142:143], v[2:3]
	ds_read2st64_b64 v[134:137], v138 offset0:36 offset1:38
	s_waitcnt vmcnt(14)
	v_pk_fma_f32 v[144:145], v[42:43], v[140:141], v[144:145]
	v_pk_fma_f32 v[164:165], v[46:47], v[140:141], v[164:165]
	v_pk_fma_f32 v[166:167], v[124:125], v[140:141], v[166:167]
	v_pk_fma_f32 v[168:169], v[126:127], v[140:141], v[168:169]
	v_pk_fma_f32 v[170:171], v[130:131], v[140:141], v[170:171]
	v_pk_fma_f32 v[172:173], v[132:133], v[140:141], v[172:173]
	v_pk_fma_f32 v[162:163], v[132:133], v[142:143], v[162:163]
	s_waitcnt lgkmcnt(0)
	v_pk_fma_f32 v[2:3], v[132:133], v[134:135], v[2:3]
	s_waitcnt vmcnt(13)
	v_pk_fma_f32 v[140:141], v[40:41], v[142:143], v[144:145]
	v_pk_fma_f32 v[144:145], v[42:43], v[142:143], v[164:165]
	v_pk_fma_f32 v[164:165], v[46:47], v[142:143], v[166:167]
	v_pk_fma_f32 v[166:167], v[124:125], v[142:143], v[168:169]
	v_pk_fma_f32 v[168:169], v[126:127], v[142:143], v[170:171]
	v_pk_fma_f32 v[170:171], v[130:131], v[142:143], v[172:173]
	v_pk_fma_f32 v[162:163], v[130:131], v[134:135], v[162:163]
	v_pk_fma_f32 v[2:3], v[130:131], v[136:137], v[2:3]
	ds_read2st64_b64 v[130:133], v138 offset0:40 offset1:42
	s_waitcnt vmcnt(12)
	v_pk_fma_f32 v[140:141], v[38:39], v[134:135], v[140:141]
	v_pk_fma_f32 v[142:143], v[40:41], v[134:135], v[144:145]
	v_pk_fma_f32 v[144:145], v[42:43], v[134:135], v[164:165]
	v_pk_fma_f32 v[164:165], v[46:47], v[134:135], v[166:167]
	v_pk_fma_f32 v[166:167], v[124:125], v[134:135], v[168:169]
	v_pk_fma_f32 v[168:169], v[126:127], v[134:135], v[170:171]
	v_pk_fma_f32 v[162:163], v[126:127], v[136:137], v[162:163]
	s_waitcnt lgkmcnt(0)
	v_pk_fma_f32 v[2:3], v[126:127], v[130:131], v[2:3]
	s_waitcnt vmcnt(11)
	v_pk_fma_f32 v[134:135], v[34:35], v[136:137], v[140:141]
	v_pk_fma_f32 v[140:141], v[38:39], v[136:137], v[142:143]
	v_pk_fma_f32 v[142:143], v[40:41], v[136:137], v[144:145]
	v_pk_fma_f32 v[144:145], v[42:43], v[136:137], v[164:165]
	v_pk_fma_f32 v[164:165], v[46:47], v[136:137], v[166:167]
	v_pk_fma_f32 v[166:167], v[124:125], v[136:137], v[168:169]
	v_pk_fma_f32 v[162:163], v[124:125], v[130:131], v[162:163]
	v_pk_fma_f32 v[2:3], v[124:125], v[132:133], v[2:3]
	ds_read2st64_b64 v[124:127], v138 offset0:44 offset1:46
	s_waitcnt vmcnt(10)
	v_pk_fma_f32 v[134:135], v[32:33], v[130:131], v[134:135]
	v_pk_fma_f32 v[136:137], v[34:35], v[130:131], v[140:141]
	v_pk_fma_f32 v[140:141], v[38:39], v[130:131], v[142:143]
	v_pk_fma_f32 v[142:143], v[40:41], v[130:131], v[144:145]
	v_pk_fma_f32 v[144:145], v[42:43], v[130:131], v[164:165]
	v_pk_fma_f32 v[164:165], v[46:47], v[130:131], v[166:167]
	s_waitcnt vmcnt(9)
	v_pk_fma_f32 v[130:131], v[30:31], v[132:133], v[134:135]
	v_pk_fma_f32 v[134:135], v[32:33], v[132:133], v[136:137]
	v_pk_fma_f32 v[136:137], v[34:35], v[132:133], v[140:141]
	v_pk_fma_f32 v[140:141], v[38:39], v[132:133], v[142:143]
	v_pk_fma_f32 v[142:143], v[40:41], v[132:133], v[144:145]
	v_pk_fma_f32 v[144:145], v[42:43], v[132:133], v[164:165]
	v_pk_fma_f32 v[162:163], v[46:47], v[132:133], v[162:163]
	s_waitcnt vmcnt(8) lgkmcnt(0)
	v_pk_fma_f32 v[130:131], v[26:27], v[124:125], v[130:131]
	v_pk_fma_f32 v[132:133], v[30:31], v[124:125], v[134:135]
	v_pk_fma_f32 v[134:135], v[32:33], v[124:125], v[136:137]
	v_pk_fma_f32 v[136:137], v[34:35], v[124:125], v[140:141]
	v_pk_fma_f32 v[140:141], v[38:39], v[124:125], v[142:143]
	v_pk_fma_f32 v[142:143], v[40:41], v[124:125], v[144:145]
	v_pk_fma_f32 v[144:145], v[42:43], v[124:125], v[162:163]
	v_pk_fma_f32 v[2:3], v[46:47], v[124:125], v[2:3]
	s_waitcnt vmcnt(7)
	v_pk_fma_f32 v[46:47], v[24:25], v[126:127], v[130:131]
	v_pk_fma_f32 v[130:131], v[26:27], v[126:127], v[132:133]
	v_pk_fma_f32 v[132:133], v[30:31], v[126:127], v[134:135]
	v_pk_fma_f32 v[134:135], v[32:33], v[126:127], v[136:137]
	v_pk_fma_f32 v[136:137], v[34:35], v[126:127], v[140:141]
	v_pk_fma_f32 v[140:141], v[38:39], v[126:127], v[142:143]
	v_pk_fma_f32 v[142:143], v[40:41], v[126:127], v[144:145]
	v_pk_fma_f32 v[2:3], v[42:43], v[126:127], v[2:3]
	ds_read2st64_b64 v[124:127], v138 offset0:48 offset1:50
	s_waitcnt lgkmcnt(0)
	v_pk_fma_f32 v[2:3], v[40:41], v[124:125], v[2:3]
	s_waitcnt vmcnt(6)
	v_pk_fma_f32 v[42:43], v[22:23], v[124:125], v[46:47]
	v_pk_fma_f32 v[46:47], v[24:25], v[124:125], v[130:131]
	v_pk_fma_f32 v[130:131], v[26:27], v[124:125], v[132:133]
	v_pk_fma_f32 v[132:133], v[30:31], v[124:125], v[134:135]
	v_pk_fma_f32 v[134:135], v[32:33], v[124:125], v[136:137]
	v_pk_fma_f32 v[136:137], v[34:35], v[124:125], v[140:141]
	v_pk_fma_f32 v[140:141], v[38:39], v[124:125], v[142:143]
	v_pk_fma_f32 v[2:3], v[38:39], v[126:127], v[2:3]
	ds_read2st64_b64 v[38:41], v138 offset0:52 offset1:54
	v_pk_fma_f32 v[124:125], v[24:25], v[126:127], v[130:131]
	v_pk_fma_f32 v[130:131], v[26:27], v[126:127], v[132:133]
	v_pk_fma_f32 v[132:133], v[30:31], v[126:127], v[134:135]
	v_pk_fma_f32 v[134:135], v[32:33], v[126:127], v[136:137]
	v_pk_fma_f32 v[136:137], v[34:35], v[126:127], v[140:141]
	s_waitcnt lgkmcnt(0)
	v_pk_fma_f32 v[2:3], v[34:35], v[38:39], v[2:3]
	s_waitcnt vmcnt(5)
	v_pk_fma_f32 v[42:43], v[18:19], v[126:127], v[42:43]
	v_pk_fma_f32 v[46:47], v[22:23], v[126:127], v[46:47]
	v_pk_fma_f32 v[126:127], v[24:25], v[38:39], v[130:131]
	v_pk_fma_f32 v[130:131], v[26:27], v[38:39], v[132:133]
	v_pk_fma_f32 v[132:133], v[30:31], v[38:39], v[134:135]
	v_pk_fma_f32 v[134:135], v[32:33], v[38:39], v[136:137]
	v_pk_fma_f32 v[2:3], v[32:33], v[40:41], v[2:3]
	ds_read2st64_b64 v[32:35], v138 offset0:56 offset1:58
	s_waitcnt vmcnt(4)
	v_pk_fma_f32 v[42:43], v[16:17], v[38:39], v[42:43]
	v_pk_fma_f32 v[46:47], v[18:19], v[38:39], v[46:47]
	v_pk_fma_f32 v[124:125], v[22:23], v[38:39], v[124:125]
	s_waitcnt vmcnt(3)
	v_pk_fma_f32 v[38:39], v[14:15], v[40:41], v[42:43]
	v_pk_fma_f32 v[42:43], v[16:17], v[40:41], v[46:47]
	v_pk_fma_f32 v[46:47], v[18:19], v[40:41], v[124:125]
	v_pk_fma_f32 v[124:125], v[22:23], v[40:41], v[126:127]
	v_pk_fma_f32 v[126:127], v[24:25], v[40:41], v[130:131]
	v_pk_fma_f32 v[130:131], v[26:27], v[40:41], v[132:133]
	v_pk_fma_f32 v[132:133], v[30:31], v[40:41], v[134:135]
	s_waitcnt vmcnt(2) lgkmcnt(0)
	v_pk_fma_f32 v[38:39], v[6:7], v[32:33], v[38:39]
	v_pk_fma_f32 v[40:41], v[14:15], v[32:33], v[42:43]
	v_pk_fma_f32 v[42:43], v[16:17], v[32:33], v[46:47]
	v_pk_fma_f32 v[46:47], v[18:19], v[32:33], v[124:125]
	v_pk_fma_f32 v[124:125], v[22:23], v[32:33], v[126:127]
	v_pk_fma_f32 v[126:127], v[24:25], v[32:33], v[130:131]
	v_pk_fma_f32 v[130:131], v[26:27], v[32:33], v[132:133]
	v_pk_fma_f32 v[2:3], v[30:31], v[32:33], v[2:3]
	ds_read2st64_b64 v[30:33], v138 offset0:60 offset1:62
	s_waitcnt vmcnt(1)
	v_pk_fma_f32 v[38:39], v[0:1], v[34:35], v[38:39]
	v_pk_fma_f32 v[40:41], v[6:7], v[34:35], v[40:41]
	v_pk_fma_f32 v[42:43], v[14:15], v[34:35], v[42:43]
	v_pk_fma_f32 v[46:47], v[16:17], v[34:35], v[46:47]
	v_pk_fma_f32 v[124:125], v[18:19], v[34:35], v[124:125]
	v_pk_fma_f32 v[126:127], v[22:23], v[34:35], v[126:127]
	v_pk_fma_f32 v[130:131], v[24:25], v[34:35], v[130:131]
	v_pk_fma_f32 v[2:3], v[26:27], v[34:35], v[2:3]
	s_waitcnt vmcnt(0) lgkmcnt(0)
	v_pk_fma_f32 v[142:143], v[4:5], v[30:31], v[38:39]
	v_pk_fma_f32 v[26:27], v[0:1], v[30:31], v[40:41]
	v_pk_fma_f32 v[34:35], v[6:7], v[30:31], v[42:43]
	v_pk_fma_f32 v[38:39], v[14:15], v[30:31], v[46:47]
	v_pk_fma_f32 v[40:41], v[16:17], v[30:31], v[124:125]
	v_pk_fma_f32 v[42:43], v[18:19], v[30:31], v[126:127]
	v_pk_fma_f32 v[46:47], v[22:23], v[30:31], v[130:131]
	v_pk_fma_f32 v[2:3], v[24:25], v[30:31], v[2:3]
	v_pk_fma_f32 v[136:137], v[4:5], v[32:33], v[26:27]
	v_pk_fma_f32 v[26:27], v[0:1], v[32:33], v[34:35]
	v_pk_fma_f32 v[30:31], v[6:7], v[32:33], v[38:39]
	v_pk_fma_f32 v[34:35], v[14:15], v[32:33], v[40:41]
	v_pk_fma_f32 v[38:39], v[16:17], v[32:33], v[42:43]
	v_pk_fma_f32 v[40:41], v[18:19], v[32:33], v[46:47]
	v_pk_fma_f32 v[2:3], v[22:23], v[32:33], v[2:3]
	ds_read2st64_b64 v[22:25], v138 offset0:64 offset1:66
	v_pk_mul_f32 v[162:163], v[128:129], v[128:129]
	v_pk_mul_f32 v[144:145], v[142:143], v[142:143]
	v_mov_b32_e32 v164, v162
	v_mov_b32_e32 v165, v128
	s_waitcnt lgkmcnt(0)
	v_pk_fma_f32 v[2:3], v[18:19], v[22:23], v[2:3]
	v_pk_fma_f32 v[130:131], v[4:5], v[22:23], v[26:27]
	v_pk_fma_f32 v[26:27], v[0:1], v[22:23], v[30:31]
	v_pk_fma_f32 v[30:31], v[6:7], v[22:23], v[34:35]
	v_pk_fma_f32 v[34:35], v[16:17], v[22:23], v[40:41]
	v_pk_fma_f32 v[2:3], v[16:17], v[24:25], v[2:3]
	ds_read2st64_b64 v[16:19], v138 offset0:68 offset1:70
	v_pk_fma_f32 v[32:33], v[14:15], v[22:23], v[38:39]
	v_pk_fma_f32 v[46:47], v[4:5], v[24:25], v[26:27]
	v_pk_fma_f32 v[22:23], v[0:1], v[24:25], v[30:31]
	v_pk_fma_f32 v[26:27], v[6:7], v[24:25], v[32:33]
	v_pk_fma_f32 v[30:31], v[14:15], v[24:25], v[34:35]
	s_waitcnt lgkmcnt(0)
	v_pk_fma_f32 v[38:39], v[4:5], v[16:17], v[22:23]
	v_pk_fma_f32 v[22:23], v[0:1], v[16:17], v[26:27]
	v_pk_fma_f32 v[24:25], v[6:7], v[16:17], v[30:31]
	v_pk_fma_f32 v[2:3], v[14:15], v[16:17], v[2:3]
	ds_read2st64_b64 v[14:17], v138 offset0:72 offset1:74
	v_pk_fma_f32 v[2:3], v[6:7], v[18:19], v[2:3]
	v_pk_fma_f32 v[30:31], v[4:5], v[18:19], v[22:23]
	v_pk_fma_f32 v[22:23], v[0:1], v[18:19], v[24:25]
	v_mov_b32_e32 v162, v163
	s_waitcnt lgkmcnt(0)
	v_pk_fma_f32 v[0:1], v[0:1], v[14:15], v[2:3]
	v_pk_fma_f32 v[22:23], v[4:5], v[14:15], v[22:23]
	v_pk_fma_f32 v[14:15], v[4:5], v[16:17], v[0:1]
	global_load_dwordx4 v[0:3], v[50:51], off
	global_load_dwordx4 v[4:7], v[52:53], off
	v_mov_b32_e32 v163, v129
	v_pk_add_f32 v[162:163], v[164:165], v[162:163]
	v_mov_b32_e32 v164, v144
	v_mov_b32_e32 v165, v142
	v_mov_b32_e32 v144, v145
	v_mov_b32_e32 v145, v143
	v_pk_add_f32 v[144:145], v[164:165], v[144:145]
	s_mov_b32 s10, 0x3b800000
	v_pk_add_f32 v[144:145], v[162:163], v[144:145]
	s_nop 1
	v_mov_b32_dpp v163, v145 quad_perm:[1,0,3,2] row_mask:0xf bank_mask:0xf
	v_mov_b32_dpp v162, v144 quad_perm:[1,0,3,2] row_mask:0xf bank_mask:0xf
	s_or_b32 s0, s5, s3
	s_add_i32 s6, s0, s9
	s_ashr_i32 s7, s6, 31
	s_lshl_b64 s[6:7], s[6:7], 11
	s_waitcnt lgkmcnt(0)
	v_pk_add_f32 v[144:145], v[144:145], v[162:163]
	s_nop 1
	v_mov_b32_dpp v163, v145 quad_perm:[2,3,0,1] row_mask:0xf bank_mask:0xf
	v_mov_b32_dpp v162, v144 quad_perm:[2,3,0,1] row_mask:0xf bank_mask:0xf
	v_pk_mul_f32 v[140:141], v[44:45], v[44:45]
	v_pk_mul_f32 v[138:139], v[136:137], v[136:137]
	v_pk_mul_f32 v[134:135], v[36:37], v[36:37]
	v_pk_mul_f32 v[132:133], v[130:131], v[130:131]
	s_waitcnt lgkmcnt(0)
	v_pk_add_f32 v[144:145], v[144:145], v[162:163]
	s_nop 1
	v_mov_b32_dpp v163, v145 row_half_mirror row_mask:0xf bank_mask:0xf
	v_mov_b32_dpp v162, v144 row_half_mirror row_mask:0xf bank_mask:0xf
	v_pk_mul_f32 v[126:127], v[28:29], v[28:29]
	v_pk_mul_f32 v[124:125], v[46:47], v[46:47]
	v_pk_mul_f32 v[42:43], v[20:21], v[20:21]
	v_pk_mul_f32 v[40:41], v[38:39], v[38:39]
	s_waitcnt lgkmcnt(0)
	v_pk_add_f32 v[144:145], v[144:145], v[162:163]
	s_nop 1
	v_mov_b32_dpp v163, v145 row_ror:8 row_mask:0xf bank_mask:0xf
	v_mov_b32_dpp v162, v144 row_ror:8 row_mask:0xf bank_mask:0xf
	v_pk_mul_f32 v[34:35], v[12:13], v[12:13]
	v_pk_mul_f32 v[32:33], v[30:31], v[30:31]
	v_pk_mul_f32 v[26:27], v[10:11], v[10:11]
	v_pk_mul_f32 v[24:25], v[22:23], v[22:23]
	s_waitcnt lgkmcnt(0)
	v_pk_add_f32 v[144:145], v[144:145], v[162:163]
	v_mov_b32_e32 v163, v145
	v_mov_b32_e32 v162, v144
	s_nop 1
	v_permlane16_swap_b32_e32 v145, v163
	v_permlane16_swap_b32_e32 v144, v162
	v_pk_mul_f32 v[18:19], v[8:9], v[8:9]
	v_pk_mul_f32 v[16:17], v[14:15], v[14:15]
	s_waitcnt lgkmcnt(0)
	v_pk_add_f32 v[144:145], v[144:145], v[162:163]
	v_mov_b32_e32 v163, v145
	v_mov_b32_e32 v162, v144
	s_nop 1
	v_permlane32_swap_b32_e32 v145, v163
	v_permlane32_swap_b32_e32 v144, v162
	s_waitcnt lgkmcnt(0)
	v_pk_add_f32 v[144:145], v[144:145], v[162:163]
	s_nop 0
	v_pk_mul_f32 v[144:145], v[144:145], s[10:11] op_sel_hi:[1,0]
	s_nop 0
	v_fma_f32 v144, -v145, v145, v144
	v_max_f32_e32 v144, 0, v144
	v_add_f32_e32 v144, 0x358637bd, v144
	v_rsq_f32_e32 v144, v144
	v_sub_f32_e32 v129, v129, v145
	v_sub_f32_e32 v128, v128, v145
	v_sub_f32_e32 v143, v143, v145
	v_pk_mul_f32 v[128:129], v[128:129], v[144:145] op_sel_hi:[1,0]
	v_sub_f32_e32 v142, v142, v145
	v_pk_mul_f32 v[142:143], v[142:143], v[144:145] op_sel_hi:[1,0]
	s_waitcnt vmcnt(0)
	v_pk_fma_f32 v[128:129], v[128:129], v[0:1], v[4:5]
	s_nop 0
	v_mul_f32_e32 v144, 0xbfb8aa3b, v128
	v_mul_f32_e32 v145, 0xbfb8aa3b, v129
	v_exp_f32_e32 v144, v144
	v_exp_f32_e32 v145, v145
	v_pk_fma_f32 v[142:143], v[142:143], v[2:3], v[6:7]
	v_add_f32_e32 v144, 1.0, v144
	v_add_f32_e32 v145, 1.0, v145
	v_rcp_f32_e32 v144, v144
	v_rcp_f32_e32 v145, v145
	s_nop 0
	v_pk_mul_f32 v[128:129], v[128:129], v[144:145]
	s_nop 0
	v_cvt_pk_bf16_f32 v128, v128, v129
	v_mul_f32_e32 v129, 0xbfb8aa3b, v142
	v_exp_f32_e32 v129, v129
	s_nop 0
	v_add_f32_e32 v129, 1.0, v129
	v_rcp_f32_e32 v144, v129
	v_mul_f32_e32 v129, 0xbfb8aa3b, v143
	v_exp_f32_e32 v129, v129
	s_nop 0
	v_add_f32_e32 v129, 1.0, v129
	v_rcp_f32_e32 v145, v129
	s_nop 0
	v_pk_mul_f32 v[142:143], v[142:143], v[144:145]
	s_nop 0
	v_cvt_pk_bf16_f32 v129, v142, v143
	v_lshl_add_u64 v[142:143], v[120:121], 0, s[6:7]
	global_store_dwordx2 v[142:143], v[128:129], off
	v_mov_b32_e32 v128, v140
	v_mov_b32_e32 v129, v44
	v_mov_b32_e32 v140, v141
	v_mov_b32_e32 v141, v45
	v_pk_add_f32 v[128:129], v[128:129], v[140:141]
	v_mov_b32_e32 v140, v138
	v_mov_b32_e32 v141, v136
	v_mov_b32_e32 v138, v139
	v_mov_b32_e32 v139, v137
	v_pk_add_f32 v[138:139], v[140:141], v[138:139]
	s_add_i32 s6, s12, s0
	v_pk_add_f32 v[128:129], v[128:129], v[138:139]
	s_nop 1
	v_mov_b32_dpp v139, v129 quad_perm:[1,0,3,2] row_mask:0xf bank_mask:0xf
	v_mov_b32_dpp v138, v128 quad_perm:[1,0,3,2] row_mask:0xf bank_mask:0xf
	s_ashr_i32 s7, s6, 31
	s_lshl_b64 s[6:7], s[6:7], 11
	s_waitcnt lgkmcnt(0)
	v_pk_add_f32 v[128:129], v[128:129], v[138:139]
	s_nop 1
	v_mov_b32_dpp v139, v129 quad_perm:[2,3,0,1] row_mask:0xf bank_mask:0xf
	v_mov_b32_dpp v138, v128 quad_perm:[2,3,0,1] row_mask:0xf bank_mask:0xf
	s_waitcnt lgkmcnt(0)
	v_pk_add_f32 v[128:129], v[128:129], v[138:139]
	s_nop 1
	v_mov_b32_dpp v139, v129 row_half_mirror row_mask:0xf bank_mask:0xf
	v_mov_b32_dpp v138, v128 row_half_mirror row_mask:0xf bank_mask:0xf
	s_waitcnt lgkmcnt(0)
	v_pk_add_f32 v[128:129], v[128:129], v[138:139]
	s_nop 1
	v_mov_b32_dpp v139, v129 row_ror:8 row_mask:0xf bank_mask:0xf
	v_mov_b32_dpp v138, v128 row_ror:8 row_mask:0xf bank_mask:0xf
	s_waitcnt lgkmcnt(0)
	v_pk_add_f32 v[128:129], v[128:129], v[138:139]
	v_mov_b32_e32 v139, v129
	v_mov_b32_e32 v138, v128
	s_nop 1
	v_permlane16_swap_b32_e32 v129, v139
	v_permlane16_swap_b32_e32 v128, v138
	s_waitcnt lgkmcnt(0)
	v_pk_add_f32 v[128:129], v[128:129], v[138:139]
	v_mov_b32_e32 v139, v129
	v_mov_b32_e32 v138, v128
	s_nop 1
	v_permlane32_swap_b32_e32 v129, v139
	v_permlane32_swap_b32_e32 v128, v138
	s_waitcnt lgkmcnt(0)
	v_pk_add_f32 v[128:129], v[128:129], v[138:139]
	s_nop 0
	v_pk_mul_f32 v[128:129], v[128:129], s[10:11] op_sel_hi:[1,0]
	s_nop 0
	v_fma_f32 v128, -v129, v129, v128
	v_max_f32_e32 v128, 0, v128
	v_add_f32_e32 v128, 0x358637bd, v128
	v_rsq_f32_e32 v128, v128
	v_sub_f32_e32 v45, v45, v129
	v_sub_f32_e32 v44, v44, v129
	v_sub_f32_e32 v137, v137, v129
	v_pk_mul_f32 v[44:45], v[44:45], v[128:129] op_sel_hi:[1,0]
	v_sub_f32_e32 v136, v136, v129
	v_pk_fma_f32 v[44:45], v[44:45], v[0:1], v[4:5]
	v_pk_mul_f32 v[128:129], v[136:137], v[128:129] op_sel_hi:[1,0]
	v_mul_f32_e32 v136, 0xbfb8aa3b, v44
	v_mul_f32_e32 v137, 0xbfb8aa3b, v45
	v_exp_f32_e32 v136, v136
	v_exp_f32_e32 v137, v137
	v_pk_fma_f32 v[128:129], v[128:129], v[2:3], v[6:7]
	v_add_f32_e32 v136, 1.0, v136
	v_add_f32_e32 v137, 1.0, v137
	v_rcp_f32_e32 v136, v136
	v_rcp_f32_e32 v137, v137
	s_nop 0
	v_pk_mul_f32 v[44:45], v[44:45], v[136:137]
	s_nop 0
	v_cvt_pk_bf16_f32 v44, v44, v45
	v_mul_f32_e32 v45, 0xbfb8aa3b, v128
	v_exp_f32_e32 v45, v45
	s_nop 0
	v_add_f32_e32 v45, 1.0, v45
	v_rcp_f32_e32 v136, v45
	v_mul_f32_e32 v45, 0xbfb8aa3b, v129
	v_exp_f32_e32 v45, v45
	s_nop 0
	v_add_f32_e32 v45, 1.0, v45
	v_rcp_f32_e32 v137, v45
	s_nop 0
	v_pk_mul_f32 v[128:129], v[128:129], v[136:137]
	s_nop 0
	v_cvt_pk_bf16_f32 v45, v128, v129
	v_lshl_add_u64 v[128:129], v[120:121], 0, s[6:7]
	global_store_dwordx2 v[128:129], v[44:45], off
	v_mov_b32_e32 v44, v134
	v_mov_b32_e32 v45, v36
	v_mov_b32_e32 v128, v135
	v_mov_b32_e32 v129, v37
	v_pk_add_f32 v[44:45], v[44:45], v[128:129]
	v_mov_b32_e32 v128, v132
	v_mov_b32_e32 v129, v130
	v_mov_b32_e32 v132, v133
	v_mov_b32_e32 v133, v131
	v_pk_add_f32 v[128:129], v[128:129], v[132:133]
	s_add_i32 s6, s13, s0
	v_pk_add_f32 v[44:45], v[44:45], v[128:129]
	s_nop 1
	v_mov_b32_dpp v129, v45 quad_perm:[1,0,3,2] row_mask:0xf bank_mask:0xf
	v_mov_b32_dpp v128, v44 quad_perm:[1,0,3,2] row_mask:0xf bank_mask:0xf
	s_ashr_i32 s7, s6, 31
	s_lshl_b64 s[6:7], s[6:7], 11
	s_waitcnt lgkmcnt(0)
	v_pk_add_f32 v[44:45], v[44:45], v[128:129]
	s_nop 1
	v_mov_b32_dpp v129, v45 quad_perm:[2,3,0,1] row_mask:0xf bank_mask:0xf
	v_mov_b32_dpp v128, v44 quad_perm:[2,3,0,1] row_mask:0xf bank_mask:0xf
	s_waitcnt lgkmcnt(0)
	v_pk_add_f32 v[44:45], v[44:45], v[128:129]
	s_nop 1
	v_mov_b32_dpp v129, v45 row_half_mirror row_mask:0xf bank_mask:0xf
	v_mov_b32_dpp v128, v44 row_half_mirror row_mask:0xf bank_mask:0xf
	s_waitcnt lgkmcnt(0)
	v_pk_add_f32 v[44:45], v[44:45], v[128:129]
	s_nop 1
	v_mov_b32_dpp v129, v45 row_ror:8 row_mask:0xf bank_mask:0xf
	v_mov_b32_dpp v128, v44 row_ror:8 row_mask:0xf bank_mask:0xf
	s_waitcnt lgkmcnt(0)
	v_pk_add_f32 v[44:45], v[44:45], v[128:129]
	v_mov_b32_e32 v129, v45
	v_mov_b32_e32 v128, v44
	s_nop 1
	v_permlane16_swap_b32_e32 v45, v129
	v_permlane16_swap_b32_e32 v44, v128
	s_waitcnt lgkmcnt(0)
	v_pk_add_f32 v[44:45], v[44:45], v[128:129]
	v_mov_b32_e32 v129, v45
	v_mov_b32_e32 v128, v44
	s_nop 1
	v_permlane32_swap_b32_e32 v45, v129
	v_permlane32_swap_b32_e32 v44, v128
	s_waitcnt lgkmcnt(0)
	v_pk_add_f32 v[44:45], v[44:45], v[128:129]
	s_nop 0
	v_pk_mul_f32 v[44:45], v[44:45], s[10:11] op_sel_hi:[1,0]
	s_nop 0
	v_fma_f32 v44, -v45, v45, v44
	v_max_f32_e32 v44, 0, v44
	v_add_f32_e32 v44, 0x358637bd, v44
	v_rsq_f32_e32 v44, v44
	v_sub_f32_e32 v37, v37, v45
	v_sub_f32_e32 v36, v36, v45
	v_sub_f32_e32 v129, v131, v45
	v_pk_mul_f32 v[36:37], v[36:37], v[44:45] op_sel_hi:[1,0]
	v_sub_f32_e32 v128, v130, v45
	v_pk_fma_f32 v[36:37], v[36:37], v[0:1], v[4:5]
	v_pk_mul_f32 v[44:45], v[128:129], v[44:45] op_sel_hi:[1,0]
	v_mul_f32_e32 v128, 0xbfb8aa3b, v36
	v_mul_f32_e32 v129, 0xbfb8aa3b, v37
	v_exp_f32_e32 v128, v128
	v_exp_f32_e32 v129, v129
	v_pk_fma_f32 v[44:45], v[44:45], v[2:3], v[6:7]
	v_add_f32_e32 v128, 1.0, v128
	v_add_f32_e32 v129, 1.0, v129
	v_rcp_f32_e32 v128, v128
	v_rcp_f32_e32 v129, v129
	s_nop 0
	v_pk_mul_f32 v[36:37], v[36:37], v[128:129]
	s_nop 0
	v_cvt_pk_bf16_f32 v36, v36, v37
	v_mul_f32_e32 v37, 0xbfb8aa3b, v44
	v_exp_f32_e32 v37, v37
	s_nop 0
	v_add_f32_e32 v37, 1.0, v37
	v_rcp_f32_e32 v128, v37
	v_mul_f32_e32 v37, 0xbfb8aa3b, v45
	v_exp_f32_e32 v37, v37
	s_nop 0
	v_add_f32_e32 v37, 1.0, v37
	v_rcp_f32_e32 v129, v37
	s_nop 0
	v_pk_mul_f32 v[44:45], v[44:45], v[128:129]
	s_nop 0
	v_cvt_pk_bf16_f32 v37, v44, v45
	v_lshl_add_u64 v[44:45], v[120:121], 0, s[6:7]
	global_store_dwordx2 v[44:45], v[36:37], off
	v_mov_b32_e32 v36, v126
	v_mov_b32_e32 v37, v28
	v_mov_b32_e32 v44, v127
	v_mov_b32_e32 v45, v29
	v_pk_add_f32 v[36:37], v[36:37], v[44:45]
	v_mov_b32_e32 v44, v124
	v_mov_b32_e32 v45, v46
	v_mov_b32_e32 v124, v125
	v_mov_b32_e32 v125, v47
	v_pk_add_f32 v[44:45], v[44:45], v[124:125]
	s_add_i32 s6, s16, s0
	v_pk_add_f32 v[36:37], v[36:37], v[44:45]
	s_nop 1
	v_mov_b32_dpp v45, v37 quad_perm:[1,0,3,2] row_mask:0xf bank_mask:0xf
	v_mov_b32_dpp v44, v36 quad_perm:[1,0,3,2] row_mask:0xf bank_mask:0xf
	s_ashr_i32 s7, s6, 31
	s_lshl_b64 s[6:7], s[6:7], 11
	s_waitcnt lgkmcnt(0)
	v_pk_add_f32 v[36:37], v[36:37], v[44:45]
	s_nop 1
	v_mov_b32_dpp v45, v37 quad_perm:[2,3,0,1] row_mask:0xf bank_mask:0xf
	v_mov_b32_dpp v44, v36 quad_perm:[2,3,0,1] row_mask:0xf bank_mask:0xf
	s_waitcnt lgkmcnt(0)
	v_pk_add_f32 v[36:37], v[36:37], v[44:45]
	s_nop 1
	v_mov_b32_dpp v45, v37 row_half_mirror row_mask:0xf bank_mask:0xf
	v_mov_b32_dpp v44, v36 row_half_mirror row_mask:0xf bank_mask:0xf
	s_waitcnt lgkmcnt(0)
	v_pk_add_f32 v[36:37], v[36:37], v[44:45]
	s_nop 1
	v_mov_b32_dpp v45, v37 row_ror:8 row_mask:0xf bank_mask:0xf
	v_mov_b32_dpp v44, v36 row_ror:8 row_mask:0xf bank_mask:0xf
	s_waitcnt lgkmcnt(0)
	v_pk_add_f32 v[36:37], v[36:37], v[44:45]
	v_mov_b32_e32 v45, v37
	v_mov_b32_e32 v44, v36
	s_nop 1
	v_permlane16_swap_b32_e32 v37, v45
	v_permlane16_swap_b32_e32 v36, v44
	s_waitcnt lgkmcnt(0)
	v_pk_add_f32 v[36:37], v[36:37], v[44:45]
	v_mov_b32_e32 v45, v37
	v_mov_b32_e32 v44, v36
	s_nop 1
	v_permlane32_swap_b32_e32 v37, v45
	v_permlane32_swap_b32_e32 v36, v44
	s_waitcnt lgkmcnt(0)
	v_pk_add_f32 v[36:37], v[36:37], v[44:45]
	s_nop 0
	v_pk_mul_f32 v[36:37], v[36:37], s[10:11] op_sel_hi:[1,0]
	s_nop 0
	v_fma_f32 v36, -v37, v37, v36
	v_max_f32_e32 v36, 0, v36
	v_add_f32_e32 v36, 0x358637bd, v36
	v_rsq_f32_e32 v36, v36
	v_sub_f32_e32 v29, v29, v37
	v_sub_f32_e32 v28, v28, v37
	v_sub_f32_e32 v45, v47, v37
	v_pk_mul_f32 v[28:29], v[28:29], v[36:37] op_sel_hi:[1,0]
	v_sub_f32_e32 v44, v46, v37
	v_pk_fma_f32 v[28:29], v[0:1], v[28:29], v[4:5]
	v_pk_mul_f32 v[36:37], v[44:45], v[36:37] op_sel_hi:[1,0]
	v_mul_f32_e32 v44, 0xbfb8aa3b, v28
	v_mul_f32_e32 v45, 0xbfb8aa3b, v29
	v_exp_f32_e32 v44, v44
	v_exp_f32_e32 v45, v45
	v_pk_fma_f32 v[36:37], v[2:3], v[36:37], v[6:7]
	v_add_f32_e32 v44, 1.0, v44
	v_add_f32_e32 v45, 1.0, v45
	v_rcp_f32_e32 v44, v44
	v_rcp_f32_e32 v45, v45
	s_nop 0
	v_pk_mul_f32 v[28:29], v[28:29], v[44:45]
	s_nop 0
	v_cvt_pk_bf16_f32 v28, v28, v29
	v_mul_f32_e32 v29, 0xbfb8aa3b, v36
	v_exp_f32_e32 v29, v29
	s_nop 0
	v_add_f32_e32 v29, 1.0, v29
	v_rcp_f32_e32 v44, v29
	v_mul_f32_e32 v29, 0xbfb8aa3b, v37
	v_exp_f32_e32 v29, v29
	s_nop 0
	v_add_f32_e32 v29, 1.0, v29
	v_rcp_f32_e32 v45, v29
	s_nop 0
	v_pk_mul_f32 v[36:37], v[36:37], v[44:45]
	s_nop 0
	v_cvt_pk_bf16_f32 v29, v36, v37
	v_lshl_add_u64 v[36:37], v[120:121], 0, s[6:7]
	global_store_dwordx2 v[36:37], v[28:29], off
	v_mov_b32_e32 v28, v42
	v_mov_b32_e32 v29, v20
	v_mov_b32_e32 v36, v43
	v_mov_b32_e32 v37, v21
	v_pk_add_f32 v[28:29], v[28:29], v[36:37]
	v_mov_b32_e32 v36, v40
	v_mov_b32_e32 v37, v38
	v_mov_b32_e32 v40, v41
	v_mov_b32_e32 v41, v39
	v_pk_add_f32 v[36:37], v[36:37], v[40:41]
	s_add_i32 s6, s17, s0
	v_pk_add_f32 v[28:29], v[28:29], v[36:37]
	s_nop 1
	v_mov_b32_dpp v37, v29 quad_perm:[1,0,3,2] row_mask:0xf bank_mask:0xf
	v_mov_b32_dpp v36, v28 quad_perm:[1,0,3,2] row_mask:0xf bank_mask:0xf
	s_ashr_i32 s7, s6, 31
	s_lshl_b64 s[6:7], s[6:7], 11
	s_waitcnt lgkmcnt(0)
	v_pk_add_f32 v[28:29], v[28:29], v[36:37]
	s_nop 1
	v_mov_b32_dpp v37, v29 quad_perm:[2,3,0,1] row_mask:0xf bank_mask:0xf
	v_mov_b32_dpp v36, v28 quad_perm:[2,3,0,1] row_mask:0xf bank_mask:0xf
	s_waitcnt lgkmcnt(0)
	v_pk_add_f32 v[28:29], v[28:29], v[36:37]
	s_nop 1
	v_mov_b32_dpp v37, v29 row_half_mirror row_mask:0xf bank_mask:0xf
	v_mov_b32_dpp v36, v28 row_half_mirror row_mask:0xf bank_mask:0xf
	s_waitcnt lgkmcnt(0)
	v_pk_add_f32 v[28:29], v[28:29], v[36:37]
	s_nop 1
	v_mov_b32_dpp v37, v29 row_ror:8 row_mask:0xf bank_mask:0xf
	v_mov_b32_dpp v36, v28 row_ror:8 row_mask:0xf bank_mask:0xf
	s_waitcnt lgkmcnt(0)
	v_pk_add_f32 v[28:29], v[28:29], v[36:37]
	v_mov_b32_e32 v37, v29
	v_mov_b32_e32 v36, v28
	s_nop 1
	v_permlane16_swap_b32_e32 v29, v37
	v_permlane16_swap_b32_e32 v28, v36
	s_waitcnt lgkmcnt(0)
	v_pk_add_f32 v[28:29], v[28:29], v[36:37]
	v_mov_b32_e32 v37, v29
	v_mov_b32_e32 v36, v28
	s_nop 1
	v_permlane32_swap_b32_e32 v29, v37
	v_permlane32_swap_b32_e32 v28, v36
	s_waitcnt lgkmcnt(0)
	v_pk_add_f32 v[28:29], v[28:29], v[36:37]
	s_nop 0
	v_pk_mul_f32 v[28:29], v[28:29], s[10:11] op_sel_hi:[1,0]
	s_nop 0
	v_fma_f32 v28, -v29, v29, v28
	v_max_f32_e32 v28, 0, v28
	v_add_f32_e32 v28, 0x358637bd, v28
	v_rsq_f32_e32 v28, v28
	v_sub_f32_e32 v21, v21, v29
	v_sub_f32_e32 v20, v20, v29
	v_sub_f32_e32 v37, v39, v29
	v_pk_mul_f32 v[20:21], v[20:21], v[28:29] op_sel_hi:[1,0]
	v_sub_f32_e32 v36, v38, v29
	v_pk_fma_f32 v[20:21], v[0:1], v[20:21], v[4:5]
	v_pk_mul_f32 v[28:29], v[36:37], v[28:29] op_sel_hi:[1,0]
	v_mul_f32_e32 v36, 0xbfb8aa3b, v20
	v_mul_f32_e32 v37, 0xbfb8aa3b, v21
	v_exp_f32_e32 v36, v36
	v_exp_f32_e32 v37, v37
	v_pk_fma_f32 v[28:29], v[2:3], v[28:29], v[6:7]
	v_add_f32_e32 v36, 1.0, v36
	v_add_f32_e32 v37, 1.0, v37
	v_rcp_f32_e32 v36, v36
	v_rcp_f32_e32 v37, v37
	s_nop 0
	v_pk_mul_f32 v[20:21], v[20:21], v[36:37]
	s_nop 0
	v_cvt_pk_bf16_f32 v20, v20, v21
	v_mul_f32_e32 v21, 0xbfb8aa3b, v28
	v_exp_f32_e32 v21, v21
	s_nop 0
	v_add_f32_e32 v21, 1.0, v21
	v_rcp_f32_e32 v36, v21
	v_mul_f32_e32 v21, 0xbfb8aa3b, v29
	v_exp_f32_e32 v21, v21
	s_nop 0
	v_add_f32_e32 v21, 1.0, v21
	v_rcp_f32_e32 v37, v21
	s_nop 0
	v_pk_mul_f32 v[28:29], v[28:29], v[36:37]
	s_nop 0
	v_cvt_pk_bf16_f32 v21, v28, v29
	v_lshl_add_u64 v[28:29], v[120:121], 0, s[6:7]
	global_store_dwordx2 v[28:29], v[20:21], off
	v_mov_b32_e32 v20, v34
	v_mov_b32_e32 v21, v12
	v_mov_b32_e32 v28, v35
	v_mov_b32_e32 v29, v13
	v_pk_add_f32 v[20:21], v[20:21], v[28:29]
	v_mov_b32_e32 v28, v32
	v_mov_b32_e32 v29, v30
	v_mov_b32_e32 v32, v33
	v_mov_b32_e32 v33, v31
	v_pk_add_f32 v[28:29], v[28:29], v[32:33]
	s_add_i32 s6, s18, s0
	v_pk_add_f32 v[20:21], v[20:21], v[28:29]
	s_nop 1
	v_mov_b32_dpp v29, v21 quad_perm:[1,0,3,2] row_mask:0xf bank_mask:0xf
	v_mov_b32_dpp v28, v20 quad_perm:[1,0,3,2] row_mask:0xf bank_mask:0xf
	s_ashr_i32 s7, s6, 31
	s_lshl_b64 s[6:7], s[6:7], 11
	s_waitcnt lgkmcnt(0)
	v_pk_add_f32 v[20:21], v[20:21], v[28:29]
	s_nop 1
	v_mov_b32_dpp v29, v21 quad_perm:[2,3,0,1] row_mask:0xf bank_mask:0xf
	v_mov_b32_dpp v28, v20 quad_perm:[2,3,0,1] row_mask:0xf bank_mask:0xf
	s_waitcnt lgkmcnt(0)
	v_pk_add_f32 v[20:21], v[20:21], v[28:29]
	s_nop 1
	v_mov_b32_dpp v29, v21 row_half_mirror row_mask:0xf bank_mask:0xf
	v_mov_b32_dpp v28, v20 row_half_mirror row_mask:0xf bank_mask:0xf
	s_waitcnt lgkmcnt(0)
	v_pk_add_f32 v[20:21], v[20:21], v[28:29]
	s_nop 1
	v_mov_b32_dpp v29, v21 row_ror:8 row_mask:0xf bank_mask:0xf
	v_mov_b32_dpp v28, v20 row_ror:8 row_mask:0xf bank_mask:0xf
	s_waitcnt lgkmcnt(0)
	v_pk_add_f32 v[20:21], v[20:21], v[28:29]
	v_mov_b32_e32 v29, v21
	v_mov_b32_e32 v28, v20
	s_nop 1
	v_permlane16_swap_b32_e32 v21, v29
	v_permlane16_swap_b32_e32 v20, v28
	s_waitcnt lgkmcnt(0)
	v_pk_add_f32 v[20:21], v[20:21], v[28:29]
	v_mov_b32_e32 v29, v21
	v_mov_b32_e32 v28, v20
	s_nop 1
	v_permlane32_swap_b32_e32 v21, v29
	v_permlane32_swap_b32_e32 v20, v28
	s_waitcnt lgkmcnt(0)
	v_pk_add_f32 v[20:21], v[20:21], v[28:29]
	s_nop 0
	v_pk_mul_f32 v[20:21], v[20:21], s[10:11] op_sel_hi:[1,0]
	s_nop 0
	v_fma_f32 v20, -v21, v21, v20
	v_max_f32_e32 v20, 0, v20
	v_add_f32_e32 v20, 0x358637bd, v20
	v_rsq_f32_e32 v20, v20
	v_sub_f32_e32 v13, v13, v21
	v_sub_f32_e32 v12, v12, v21
	v_sub_f32_e32 v29, v31, v21
	v_pk_mul_f32 v[12:13], v[12:13], v[20:21] op_sel_hi:[1,0]
	v_sub_f32_e32 v28, v30, v21
	v_pk_fma_f32 v[12:13], v[0:1], v[12:13], v[4:5]
	v_pk_mul_f32 v[20:21], v[28:29], v[20:21] op_sel_hi:[1,0]
	v_mul_f32_e32 v28, 0xbfb8aa3b, v12
	v_mul_f32_e32 v29, 0xbfb8aa3b, v13
	v_exp_f32_e32 v28, v28
	v_exp_f32_e32 v29, v29
	v_pk_fma_f32 v[20:21], v[2:3], v[20:21], v[6:7]
	v_add_f32_e32 v28, 1.0, v28
	v_add_f32_e32 v29, 1.0, v29
	v_rcp_f32_e32 v28, v28
	v_rcp_f32_e32 v29, v29
	s_nop 0
	v_pk_mul_f32 v[12:13], v[12:13], v[28:29]
	s_nop 0
	v_cvt_pk_bf16_f32 v12, v12, v13
	v_mul_f32_e32 v13, 0xbfb8aa3b, v20
	v_exp_f32_e32 v13, v13
	s_nop 0
	v_add_f32_e32 v13, 1.0, v13
	v_rcp_f32_e32 v28, v13
	v_mul_f32_e32 v13, 0xbfb8aa3b, v21
	v_exp_f32_e32 v13, v13
	s_nop 0
	v_add_f32_e32 v13, 1.0, v13
	v_rcp_f32_e32 v29, v13
	s_nop 0
	v_pk_mul_f32 v[20:21], v[20:21], v[28:29]
	s_nop 0
	v_cvt_pk_bf16_f32 v13, v20, v21
	v_lshl_add_u64 v[20:21], v[120:121], 0, s[6:7]
	global_store_dwordx2 v[20:21], v[12:13], off
	v_mov_b32_e32 v12, v26
	v_mov_b32_e32 v13, v10
	v_mov_b32_e32 v20, v27
	v_mov_b32_e32 v21, v11
	v_pk_add_f32 v[12:13], v[12:13], v[20:21]
	v_mov_b32_e32 v20, v24
	v_mov_b32_e32 v21, v22
	v_mov_b32_e32 v24, v25
	v_mov_b32_e32 v25, v23
	v_pk_add_f32 v[20:21], v[20:21], v[24:25]
	s_add_i32 s6, s19, s0
	v_pk_add_f32 v[12:13], v[12:13], v[20:21]
	s_nop 1
	v_mov_b32_dpp v21, v13 quad_perm:[1,0,3,2] row_mask:0xf bank_mask:0xf
	v_mov_b32_dpp v20, v12 quad_perm:[1,0,3,2] row_mask:0xf bank_mask:0xf
	s_ashr_i32 s7, s6, 31
	s_lshl_b64 s[6:7], s[6:7], 11
	s_add_i32 s0, s20, s0
	s_ashr_i32 s1, s0, 31
	s_waitcnt lgkmcnt(0)
	v_pk_add_f32 v[12:13], v[12:13], v[20:21]
	s_nop 1
	v_mov_b32_dpp v21, v13 quad_perm:[2,3,0,1] row_mask:0xf bank_mask:0xf
	v_mov_b32_dpp v20, v12 quad_perm:[2,3,0,1] row_mask:0xf bank_mask:0xf
	s_lshl_b64 s[0:1], s[0:1], 11
	s_cmp_lg_u32 s2, 63
	s_waitcnt lgkmcnt(0)
	v_pk_add_f32 v[12:13], v[12:13], v[20:21]
	s_nop 1
	v_mov_b32_dpp v21, v13 row_half_mirror row_mask:0xf bank_mask:0xf
	v_mov_b32_dpp v20, v12 row_half_mirror row_mask:0xf bank_mask:0xf
	s_waitcnt lgkmcnt(0)
	v_pk_add_f32 v[12:13], v[12:13], v[20:21]
	s_nop 1
	v_mov_b32_dpp v21, v13 row_ror:8 row_mask:0xf bank_mask:0xf
	v_mov_b32_dpp v20, v12 row_ror:8 row_mask:0xf bank_mask:0xf
	s_waitcnt lgkmcnt(0)
	v_pk_add_f32 v[12:13], v[12:13], v[20:21]
	v_mov_b32_e32 v21, v13
	v_mov_b32_e32 v20, v12
	s_nop 1
	v_permlane16_swap_b32_e32 v13, v21
	v_permlane16_swap_b32_e32 v12, v20
	s_waitcnt lgkmcnt(0)
	v_pk_add_f32 v[12:13], v[12:13], v[20:21]
	v_mov_b32_e32 v21, v13
	v_mov_b32_e32 v20, v12
	s_nop 1
	v_permlane32_swap_b32_e32 v13, v21
	v_permlane32_swap_b32_e32 v12, v20
	s_waitcnt lgkmcnt(0)
	v_pk_add_f32 v[12:13], v[12:13], v[20:21]
	s_nop 0
	v_pk_mul_f32 v[12:13], v[12:13], s[10:11] op_sel_hi:[1,0]
	s_nop 0
	v_fma_f32 v12, -v13, v13, v12
	v_max_f32_e32 v12, 0, v12
	v_add_f32_e32 v12, 0x358637bd, v12
	v_rsq_f32_e32 v12, v12
	v_sub_f32_e32 v11, v11, v13
	v_sub_f32_e32 v10, v10, v13
	v_sub_f32_e32 v21, v23, v13
	v_pk_mul_f32 v[10:11], v[10:11], v[12:13] op_sel_hi:[1,0]
	v_sub_f32_e32 v20, v22, v13
	v_pk_fma_f32 v[10:11], v[0:1], v[10:11], v[4:5]
	v_pk_mul_f32 v[12:13], v[20:21], v[12:13] op_sel_hi:[1,0]
	v_mul_f32_e32 v20, 0xbfb8aa3b, v10
	v_mul_f32_e32 v21, 0xbfb8aa3b, v11
	v_exp_f32_e32 v20, v20
	v_exp_f32_e32 v21, v21
	v_pk_fma_f32 v[12:13], v[2:3], v[12:13], v[6:7]
	v_add_f32_e32 v20, 1.0, v20
	v_add_f32_e32 v21, 1.0, v21
	v_rcp_f32_e32 v20, v20
	v_rcp_f32_e32 v21, v21
	s_nop 0
	v_pk_mul_f32 v[10:11], v[10:11], v[20:21]
	s_nop 0
	v_cvt_pk_bf16_f32 v10, v10, v11
	v_mul_f32_e32 v11, 0xbfb8aa3b, v12
	v_exp_f32_e32 v11, v11
	s_nop 0
	v_add_f32_e32 v11, 1.0, v11
	v_rcp_f32_e32 v20, v11
	v_mul_f32_e32 v11, 0xbfb8aa3b, v13
	v_exp_f32_e32 v11, v11
	s_nop 0
	v_add_f32_e32 v11, 1.0, v11
	v_rcp_f32_e32 v21, v11
	s_nop 0
	v_pk_mul_f32 v[12:13], v[12:13], v[20:21]
	s_nop 0
	v_cvt_pk_bf16_f32 v11, v12, v13
	v_lshl_add_u64 v[12:13], v[120:121], 0, s[6:7]
	global_store_dwordx2 v[12:13], v[10:11], off
	v_mov_b32_e32 v10, v18
	v_mov_b32_e32 v11, v8
	v_mov_b32_e32 v12, v19
	v_mov_b32_e32 v13, v9
	v_pk_add_f32 v[10:11], v[10:11], v[12:13]
	v_mov_b32_e32 v12, v16
	v_mov_b32_e32 v13, v14
	v_mov_b32_e32 v16, v17
	v_mov_b32_e32 v17, v15
	v_pk_add_f32 v[12:13], v[12:13], v[16:17]
	s_nop 0
	v_pk_add_f32 v[10:11], v[10:11], v[12:13]
	s_nop 1
	v_mov_b32_dpp v13, v11 quad_perm:[1,0,3,2] row_mask:0xf bank_mask:0xf
	v_mov_b32_dpp v12, v10 quad_perm:[1,0,3,2] row_mask:0xf bank_mask:0xf
	s_waitcnt lgkmcnt(0)
	v_pk_add_f32 v[10:11], v[10:11], v[12:13]
	s_nop 1
	v_mov_b32_dpp v13, v11 quad_perm:[2,3,0,1] row_mask:0xf bank_mask:0xf
	v_mov_b32_dpp v12, v10 quad_perm:[2,3,0,1] row_mask:0xf bank_mask:0xf
	s_waitcnt lgkmcnt(0)
	v_pk_add_f32 v[10:11], v[10:11], v[12:13]
	s_nop 1
	v_mov_b32_dpp v13, v11 row_half_mirror row_mask:0xf bank_mask:0xf
	v_mov_b32_dpp v12, v10 row_half_mirror row_mask:0xf bank_mask:0xf
	s_waitcnt lgkmcnt(0)
	v_pk_add_f32 v[10:11], v[10:11], v[12:13]
	s_nop 1
	v_mov_b32_dpp v13, v11 row_ror:8 row_mask:0xf bank_mask:0xf
	v_mov_b32_dpp v12, v10 row_ror:8 row_mask:0xf bank_mask:0xf
	s_waitcnt lgkmcnt(0)
	v_pk_add_f32 v[10:11], v[10:11], v[12:13]
	v_mov_b32_e32 v13, v11
	v_mov_b32_e32 v12, v10
	s_nop 1
	v_permlane16_swap_b32_e32 v11, v13
	v_permlane16_swap_b32_e32 v10, v12
	s_waitcnt lgkmcnt(0)
	v_pk_add_f32 v[10:11], v[10:11], v[12:13]
	v_mov_b32_e32 v13, v11
	v_mov_b32_e32 v12, v10
	s_nop 1
	v_permlane32_swap_b32_e32 v11, v13
	v_permlane32_swap_b32_e32 v10, v12
	s_waitcnt lgkmcnt(0)
	v_pk_add_f32 v[10:11], v[10:11], v[12:13]
	s_nop 0
	v_pk_mul_f32 v[10:11], v[10:11], s[10:11] op_sel_hi:[1,0]
	s_nop 0
	v_fma_f32 v10, -v11, v11, v10
	v_max_f32_e32 v10, 0, v10
	v_add_f32_e32 v10, 0x358637bd, v10
	v_rsq_f32_e32 v10, v10
	v_sub_f32_e32 v9, v9, v11
	v_sub_f32_e32 v8, v8, v11
	v_sub_f32_e32 v13, v15, v11
	v_pk_mul_f32 v[8:9], v[8:9], v[10:11] op_sel_hi:[1,0]
	v_sub_f32_e32 v12, v14, v11
	v_pk_fma_f32 v[0:1], v[0:1], v[8:9], v[4:5]
	v_pk_mul_f32 v[10:11], v[12:13], v[10:11] op_sel_hi:[1,0]
	v_mul_f32_e32 v4, 0xbfb8aa3b, v0
	v_mul_f32_e32 v5, 0xbfb8aa3b, v1
	v_exp_f32_e32 v4, v4
	v_exp_f32_e32 v5, v5
	v_pk_fma_f32 v[2:3], v[2:3], v[10:11], v[6:7]
	v_add_f32_e32 v4, 1.0, v4
	v_add_f32_e32 v5, 1.0, v5
	v_rcp_f32_e32 v4, v4
	v_rcp_f32_e32 v5, v5
	s_nop 0
	v_pk_mul_f32 v[0:1], v[0:1], v[4:5]
	s_nop 0
	v_cvt_pk_bf16_f32 v0, v0, v1
	v_mul_f32_e32 v1, 0xbfb8aa3b, v2
	v_exp_f32_e32 v1, v1
	s_nop 0
	v_add_f32_e32 v1, 1.0, v1
	v_rcp_f32_e32 v4, v1
	v_mul_f32_e32 v1, 0xbfb8aa3b, v3
	v_exp_f32_e32 v1, v1
	s_nop 0
	v_add_f32_e32 v1, 1.0, v1
	v_rcp_f32_e32 v5, v1
	s_nop 0
	v_pk_mul_f32 v[2:3], v[2:3], v[4:5]
	s_nop 0
	v_cvt_pk_bf16_f32 v1, v2, v3
	v_lshl_add_u64 v[2:3], v[120:121], 0, s[0:1]
	global_store_dwordx2 v[2:3], v[0:1], off
	s_cbranch_scc1 .LBB0_502
	s_and_saveexec_b64 s[2:3], s[46:47]
	s_cbranch_execz .LBB0_501
	v_readlane_b32 s0, v252, 11
	s_add_i32 s29, s4, s0
	s_mul_hi_i32 s28, s29, 0x7800
	s_mulk_i32 s29, 0x7800
	s_mov_b64 s[0:1], -1
	v_mov_b32_e32 v0, v122
	v_mov_b32_e32 v2, v149
	s_and_saveexec_b64 s[4:5], s[48:49]
	s_cbranch_execz .LBB0_535
	s_add_u32 s6, s21, s29
	s_addc_u32 s7, s22, s28
	s_mov_b64 s[10:11], 0
	v_mov_b32_e32 v2, v160
	v_mov_b32_e32 v3, v150
	v_mov_b64_e32 v[0:1], v[122:123]

.Lshg_join:
	v_lshlrev_b32_e32 v87, 16, v198
	v_lshlrev_b32_e32 v88, 16, v199
	v_lshlrev_b32_e32 v89, 16, v200
	v_mul_f32_e32 v78, 0xbfb8aa3b, v87
	v_exp_f32_e32 v78, v78
	v_sub_f32_e32 v87, 1.0, v76
	s_barrier
	v_add_f32_e32 v79, 1.0, v78
	v_rcp_f32_e32 v79, v79
	v_mul_f32_e32 v78, v87, v78
	v_fmac_f32_e32 v76, v87, v79
	v_mul_f32_e32 v78, v78, v79
	ds_write2st64_b32 v84, v76, v78 offset1:8
	ds_write2st64_b32 v84, v88, v89 offset0:16 offset1:24
	s_waitcnt lgkmcnt(0)
	s_barrier
	ds_read2st64_b32 v[78:79], v82 offset0:24 offset1:26
	ds_read_b128 v[88:91], v68
	ds_read_b128 v[100:103], v68 offset:16
	ds_read_b128 v[104:107], v68 offset:32
	ds_read_b128 v[108:111], v68 offset:48
	ds_read_b128 v[92:95], v68 offset:2048
	ds_read_b128 v[112:115], v68 offset:4096
	s_waitcnt lgkmcnt(1)
	v_mul_f32_e32 v98, v78, v92
	v_mul_f32_e32 v92, v78, v93
	v_mul_f32_e32 v93, v78, v94
	v_mul_f32_e32 v94, v78, v95
	v_fmac_f32_e32 v98, v32, v88
	v_fmac_f32_e32 v92, v33, v89
	v_fmac_f32_e32 v93, v34, v90
	v_fmac_f32_e32 v94, v35, v91
	ds_read_b128 v[88:91], v68 offset:2064
	s_waitcnt lgkmcnt(1)
	v_fma_f32 v32, v112, v98, 0
	v_fmac_f32_e32 v32, v113, v92
	v_fmac_f32_e32 v32, v114, v93
	v_fmac_f32_e32 v32, v115, v94
	ds_read_b128 v[112:115], v68 offset:4112
	s_waitcnt lgkmcnt(1)
	v_mul_f32_e32 v97, v78, v88
	v_mul_f32_e32 v88, v78, v89
	v_fmac_f32_e32 v97, v36, v100
	v_fmac_f32_e32 v88, v37, v101
	ds_read_b128 v[34:37], v68 offset:2080
	v_mul_f32_e32 v87, v78, v90
	v_mul_f32_e32 v76, v78, v91
	v_fmac_f32_e32 v87, v38, v102
	v_fmac_f32_e32 v76, v39, v103
	ds_read_b128 v[100:103], v68 offset:4128
	s_waitcnt lgkmcnt(2)
	v_fmac_f32_e32 v32, v112, v97
	v_fmac_f32_e32 v32, v113, v88
	v_fmac_f32_e32 v32, v114, v87
	s_waitcnt lgkmcnt(1)
	v_mul_f32_e32 v96, v78, v34
	v_fmac_f32_e32 v32, v115, v76
	v_fmac_f32_e32 v96, v40, v104
	v_mul_f32_e32 v89, v78, v35
	v_fmac_f32_e32 v89, v41, v105
	v_mul_f32_e32 v90, v78, v36
	ds_read_b128 v[38:41], v68 offset:2096
	s_waitcnt lgkmcnt(1)
	v_fmac_f32_e32 v32, v100, v96
	v_fmac_f32_e32 v32, v101, v89
	v_fmac_f32_e32 v90, v42, v106
	v_mul_f32_e32 v91, v78, v37
	v_fmac_f32_e32 v32, v102, v90
	v_fmac_f32_e32 v91, v43, v107
	v_fmac_f32_e32 v32, v103, v91
	ds_read_b128 v[100:103], v68 offset:4144
	s_waitcnt lgkmcnt(1)
	v_mul_f32_e32 v95, v78, v38
	v_fmac_f32_e32 v95, v44, v108
	v_mul_f32_e32 v38, v78, v39
	v_fmac_f32_e32 v38, v45, v109
	s_waitcnt lgkmcnt(0)
	v_fmac_f32_e32 v32, v100, v95
	v_mul_f32_e32 v37, v78, v40
	v_mul_f32_e32 v36, v78, v41
	v_fmac_f32_e32 v32, v101, v38
	v_fmac_f32_e32 v37, v46, v110
	v_fmac_f32_e32 v36, v47, v111
	ds_read_b128 v[40:43], v68 offset:64
	ds_read_b128 v[44:47], v68 offset:2112
	v_fmac_f32_e32 v32, v102, v37
	v_fmac_f32_e32 v32, v103, v36
	ds_read_b128 v[100:103], v68 offset:4160
	s_waitcnt lgkmcnt(1)
	v_mul_f32_e32 v44, v78, v44
	v_fmac_f32_e32 v44, v48, v40
	v_mul_f32_e32 v39, v78, v45
	s_waitcnt lgkmcnt(0)
	v_fmac_f32_e32 v32, v100, v44
	v_fmac_f32_e32 v39, v49, v41
	v_mul_f32_e32 v40, v78, v46
	v_fmac_f32_e32 v32, v101, v39
	v_fmac_f32_e32 v40, v50, v42
	v_mul_f32_e32 v41, v78, v47
	v_fmac_f32_e32 v32, v102, v40
	v_fmac_f32_e32 v41, v51, v43
	v_fmac_f32_e32 v32, v103, v41
	ds_read_b128 v[46:49], v68 offset:80
	ds_read_b128 v[100:103], v68 offset:2128
	ds_read_b128 v[104:107], v68 offset:4176
	s_waitcnt lgkmcnt(1)
	v_mul_f32_e32 v45, v78, v100
	v_fmac_f32_e32 v45, v52, v46
	v_mul_f32_e32 v42, v78, v101
	v_mul_f32_e32 v43, v78, v102
	v_mul_f32_e32 v46, v78, v103
	v_fmac_f32_e32 v42, v53, v47
	v_fmac_f32_e32 v43, v54, v48
	v_fmac_f32_e32 v46, v55, v49
	ds_read_b128 v[48:51], v68 offset:96
	ds_read_b128 v[52:55], v68 offset:2144
	ds_read_b128 v[100:103], v68 offset:4192
	s_waitcnt lgkmcnt(3)
	v_fmac_f32_e32 v32, v104, v45
	v_fmac_f32_e32 v32, v105, v42
	v_fmac_f32_e32 v32, v106, v43
	s_waitcnt lgkmcnt(1)
	v_mul_f32_e32 v47, v78, v52
	v_fmac_f32_e32 v32, v107, v46
	v_fmac_f32_e32 v47, v56, v48
	v_mul_f32_e32 v99, v78, v53
	s_waitcnt lgkmcnt(0)
	v_fmac_f32_e32 v32, v100, v47
	v_fmac_f32_e32 v99, v57, v49
	v_fmac_f32_e32 v32, v101, v99
	v_mul_f32_e32 v100, v78, v54
	v_mul_f32_e32 v101, v78, v55
	v_fmac_f32_e32 v100, v58, v50
	v_fmac_f32_e32 v101, v59, v51
	ds_read_b128 v[52:55], v68 offset:112
	ds_read_b128 v[56:59], v68 offset:2160
	ds_read_b128 v[104:107], v68 offset:4208
	v_fmac_f32_e32 v32, v102, v100
	v_fmac_f32_e32 v32, v103, v101
	s_waitcnt lgkmcnt(1)
	v_mul_f32_e32 v102, v78, v56
	v_fmac_f32_e32 v102, v60, v52
	v_mul_f32_e32 v51, v78, v57
	s_waitcnt lgkmcnt(0)
	v_fmac_f32_e32 v32, v104, v102
	v_fmac_f32_e32 v51, v61, v53
	v_mul_f32_e32 v52, v78, v58
	v_fmac_f32_e32 v32, v105, v51
	v_fmac_f32_e32 v52, v62, v54
	v_mul_f32_e32 v53, v78, v59
	v_fmac_f32_e32 v32, v106, v52
	v_fmac_f32_e32 v53, v63, v55
	v_fmac_f32_e32 v32, v107, v53
	ds_write_b32 v86, v32 offset:8192
	ds_read_b128 v[56:59], v68 offset:512
	ds_read_b128 v[60:63], v68 offset:528
	ds_read_b128 v[104:107], v68 offset:544
	ds_read_b128 v[32:35], v68 offset:560
	ds_read_b128 v[108:111], v68 offset:2560
	ds_read_b128 v[112:115], v68 offset:4608
	s_waitcnt lgkmcnt(1)
	v_mul_f32_e32 v54, v79, v108
	v_mul_f32_e32 v55, v79, v109
	v_fmac_f32_e32 v54, v98, v56
	v_fmac_f32_e32 v55, v92, v57
	v_mul_f32_e32 v56, v79, v110
	v_mul_f32_e32 v57, v79, v111
	ds_read_b128 v[108:111], v68 offset:2576
	s_waitcnt lgkmcnt(1)
	v_fma_f32 v98, v112, v54, 0
	v_fmac_f32_e32 v98, v113, v55
	v_fmac_f32_e32 v56, v93, v58
	v_fmac_f32_e32 v98, v114, v56
	v_fmac_f32_e32 v57, v94, v59
	s_waitcnt lgkmcnt(0)
	v_mul_f32_e32 v58, v79, v108
	v_mul_f32_e32 v48, v79, v109
	v_mul_f32_e32 v49, v79, v110
	v_mul_f32_e32 v59, v79, v111
	v_fmac_f32_e32 v98, v115, v57
	v_fmac_f32_e32 v58, v97, v60
	ds_read_b128 v[112:115], v68 offset:4624
	v_fmac_f32_e32 v48, v88, v61
	v_fmac_f32_e32 v49, v87, v62
	v_fmac_f32_e32 v59, v76, v63
	ds_read_b128 v[60:63], v68 offset:2592
	ds_read_b128 v[108:111], v68 offset:4640
	s_waitcnt lgkmcnt(2)
	v_fmac_f32_e32 v98, v112, v58
	v_fmac_f32_e32 v98, v113, v48
	v_fmac_f32_e32 v98, v114, v49
	s_waitcnt lgkmcnt(1)
	v_mul_f32_e32 v61, v79, v61
	v_mul_f32_e32 v62, v79, v62
	v_mul_f32_e32 v63, v79, v63
	v_fmac_f32_e32 v61, v89, v105
	v_fmac_f32_e32 v62, v90, v106
	v_fmac_f32_e32 v63, v91, v107
	ds_read_b128 v[88:91], v68 offset:2608
	v_mul_f32_e32 v60, v79, v60
	v_fmac_f32_e32 v98, v115, v59
	v_fmac_f32_e32 v60, v96, v104
	s_waitcnt lgkmcnt(1)
	v_fmac_f32_e32 v98, v108, v60
	s_waitcnt lgkmcnt(0)
	v_mul_f32_e32 v76, v79, v88
	v_fmac_f32_e32 v76, v95, v32
	ds_read_b128 v[92:95], v68 offset:4656
	v_fmac_f32_e32 v98, v109, v61
	v_fmac_f32_e32 v98, v110, v62
	v_fmac_f32_e32 v98, v111, v63
	v_mul_f32_e32 v50, v79, v89
	s_waitcnt lgkmcnt(0)
	v_fmac_f32_e32 v98, v92, v76
	v_fmac_f32_e32 v50, v38, v33
	v_mul_f32_e32 v38, v79, v90
	v_mul_f32_e32 v78, v79, v91
	v_fmac_f32_e32 v98, v93, v50
	v_fmac_f32_e32 v38, v37, v34
	v_fmac_f32_e32 v78, v36, v35
	ds_read_b128 v[32:35], v68 offset:576
	ds_read_b128 v[88:91], v68 offset:2624
	v_fmac_f32_e32 v98, v94, v38
	v_fmac_f32_e32 v98, v95, v78
	ds_read_b128 v[92:95], v68 offset:4672
	s_waitcnt lgkmcnt(1)
	v_mul_f32_e32 v87, v79, v88
	v_fmac_f32_e32 v87, v44, v32
	v_mul_f32_e32 v44, v79, v89
	s_waitcnt lgkmcnt(0)
	v_fmac_f32_e32 v98, v92, v87
	v_fmac_f32_e32 v44, v39, v33
	v_mul_f32_e32 v88, v79, v90
	v_mul_f32_e32 v89, v79, v91
	v_fmac_f32_e32 v98, v93, v44
	v_fmac_f32_e32 v88, v40, v34
	v_fmac_f32_e32 v89, v41, v35
	ds_read_b128 v[32:35], v68 offset:592
	ds_read_b128 v[90:93], v68 offset:2640
	v_fmac_f32_e32 v98, v94, v88
	v_fmac_f32_e32 v98, v95, v89
	ds_read_b128 v[94:97], v68 offset:4688
	s_waitcnt lgkmcnt(1)
	v_mul_f32_e32 v90, v79, v90
	v_fmac_f32_e32 v90, v45, v32
	v_mul_f32_e32 v39, v79, v91
	s_waitcnt lgkmcnt(0)
	v_fmac_f32_e32 v98, v94, v90
	v_fmac_f32_e32 v39, v42, v33
	v_mul_f32_e32 v40, v79, v92
	v_mul_f32_e32 v45, v79, v93
	v_fmac_f32_e32 v98, v95, v39
	v_fmac_f32_e32 v40, v43, v34
	v_fmac_f32_e32 v45, v46, v35
	ds_read_b128 v[32:35], v68 offset:608
	ds_read_b128 v[92:95], v68 offset:2656
	v_fmac_f32_e32 v98, v96, v40
	v_fmac_f32_e32 v98, v97, v45
	ds_read_b128 v[104:107], v68 offset:4704
	s_waitcnt lgkmcnt(1)
	v_mul_f32_e32 v46, v79, v92
	v_fmac_f32_e32 v46, v47, v32
	v_mul_f32_e32 v47, v79, v93
	v_mul_f32_e32 v91, v79, v94
	v_mul_f32_e32 v92, v79, v95
	v_fmac_f32_e32 v47, v99, v33
	v_fmac_f32_e32 v91, v100, v34
	v_fmac_f32_e32 v92, v101, v35
	ds_read_b128 v[32:35], v68 offset:624
	ds_read_b128 v[94:97], v68 offset:2672
	s_waitcnt lgkmcnt(2)
	v_fmac_f32_e32 v98, v104, v46
	v_fmac_f32_e32 v98, v105, v47
	v_fmac_f32_e32 v98, v106, v91
	v_fmac_f32_e32 v98, v107, v92
	s_waitcnt lgkmcnt(0)
	v_mul_f32_e32 v93, v79, v94
	v_fmac_f32_e32 v93, v102, v32
	ds_read_b128 v[100:103], v68 offset:4720
	v_mul_f32_e32 v41, v79, v95
	v_fmac_f32_e32 v41, v51, v33
	v_mul_f32_e32 v42, v79, v96
	v_fmac_f32_e32 v42, v52, v34
	s_waitcnt lgkmcnt(0)
	v_fmac_f32_e32 v98, v100, v93
	v_fmac_f32_e32 v98, v101, v41
	v_mul_f32_e32 v43, v79, v97
	v_fmac_f32_e32 v98, v102, v42
	v_fmac_f32_e32 v43, v53, v35
	v_fmac_f32_e32 v98, v103, v43
	ds_write_b32 v86, v98 offset:8704
	ds_read2st64_b32 v[36:37], v82 offset0:28 offset1:30
	ds_read_b128 v[94:97], v68 offset:1024
	ds_read_b128 v[98:101], v68 offset:1040
	ds_read_b128 v[102:105], v68 offset:1056
	ds_read_b128 v[32:35], v68 offset:1072
	ds_read_b128 v[106:109], v68 offset:3072
	ds_read_b128 v[110:113], v68 offset:5120
	s_waitcnt lgkmcnt(1)
	v_mul_f32_e32 v52, v36, v106
	v_mul_f32_e32 v53, v36, v107
	v_fmac_f32_e32 v52, v54, v94
	v_fmac_f32_e32 v53, v55, v95
	v_mul_f32_e32 v54, v36, v108
	v_mul_f32_e32 v55, v36, v109
	ds_read_b128 v[106:109], v68 offset:3088
	s_waitcnt lgkmcnt(1)
	v_fma_f32 v94, v110, v52, 0
	v_fmac_f32_e32 v94, v111, v53
	v_fmac_f32_e32 v54, v56, v96
	v_fmac_f32_e32 v94, v112, v54
	v_fmac_f32_e32 v55, v57, v97
	s_waitcnt lgkmcnt(0)
	v_mul_f32_e32 v56, v36, v106
	v_mul_f32_e32 v51, v36, v107
	v_fmac_f32_e32 v94, v113, v55
	v_fmac_f32_e32 v56, v58, v98
	ds_read_b128 v[110:113], v68 offset:5136
	v_fmac_f32_e32 v51, v48, v99
	ds_read_b128 v[96:99], v68 offset:3104
	v_mul_f32_e32 v48, v36, v108
	v_mul_f32_e32 v57, v36, v109
	ds_read_b128 v[106:109], v68 offset:5152
	s_waitcnt lgkmcnt(2)
	v_fmac_f32_e32 v94, v110, v56
	v_fmac_f32_e32 v57, v59, v101
	s_waitcnt lgkmcnt(1)
	v_mul_f32_e32 v58, v36, v96
	v_mul_f32_e32 v59, v36, v97
	v_fmac_f32_e32 v94, v111, v51
	v_fmac_f32_e32 v48, v49, v100
	v_fmac_f32_e32 v58, v60, v102
	v_fmac_f32_e32 v59, v61, v103
	v_mul_f32_e32 v60, v36, v98
	v_mul_f32_e32 v61, v36, v99
	ds_read_b128 v[96:99], v68 offset:3120
	v_fmac_f32_e32 v94, v112, v48
	v_fmac_f32_e32 v94, v113, v57
	ds_read_b128 v[100:103], v68 offset:5168
	s_waitcnt lgkmcnt(2)
	v_fmac_f32_e32 v94, v106, v58
	v_fmac_f32_e32 v94, v107, v59
	v_fmac_f32_e32 v60, v62, v104
	v_fmac_f32_e32 v94, v108, v60
	v_fmac_f32_e32 v61, v63, v105
	s_waitcnt lgkmcnt(1)
	v_mul_f32_e32 v62, v36, v96
	v_fmac_f32_e32 v94, v109, v61
	v_fmac_f32_e32 v62, v76, v32
	v_mul_f32_e32 v49, v36, v97
	s_waitcnt lgkmcnt(0)
	v_fmac_f32_e32 v94, v100, v62
	v_fmac_f32_e32 v49, v50, v33
	v_mul_f32_e32 v50, v36, v98
	v_mul_f32_e32 v63, v36, v99
	v_fmac_f32_e32 v94, v101, v49
	v_fmac_f32_e32 v50, v38, v34
	v_fmac_f32_e32 v63, v78, v35
	ds_read_b128 v[32:35], v68 offset:1088
	ds_read_b128 v[96:99], v68 offset:3136
	v_fmac_f32_e32 v94, v102, v50
	v_fmac_f32_e32 v94, v103, v63
	ds_read_b128 v[100:103], v68 offset:5184
	s_waitcnt lgkmcnt(1)
	v_mul_f32_e32 v76, v36, v96
	v_fmac_f32_e32 v76, v87, v32
	v_mul_f32_e32 v78, v36, v97
	s_waitcnt lgkmcnt(0)
	v_fmac_f32_e32 v94, v100, v76
	v_fmac_f32_e32 v78, v44, v33
	v_mul_f32_e32 v44, v36, v98
	v_mul_f32_e32 v79, v36, v99
	v_fmac_f32_e32 v94, v101, v78
	v_fmac_f32_e32 v44, v88, v34
	v_fmac_f32_e32 v79, v89, v35
	ds_read_b128 v[32:35], v68 offset:1104
	ds_read_b128 v[96:99], v68 offset:3152
	v_fmac_f32_e32 v94, v102, v44
	v_fmac_f32_e32 v94, v103, v79
	ds_read_b128 v[100:103], v68 offset:5200
	s_waitcnt lgkmcnt(1)
	v_mul_f32_e32 v87, v36, v96
	v_fmac_f32_e32 v87, v90, v32
	v_mul_f32_e32 v38, v36, v97
	s_waitcnt lgkmcnt(0)
	v_fmac_f32_e32 v94, v100, v87
	v_fmac_f32_e32 v38, v39, v33
	v_mul_f32_e32 v39, v36, v98
	v_mul_f32_e32 v88, v36, v99
	v_fmac_f32_e32 v94, v101, v38
	v_fmac_f32_e32 v39, v40, v34
	v_fmac_f32_e32 v88, v45, v35
	ds_read_b128 v[32:35], v68 offset:1120
	ds_read_b128 v[96:99], v68 offset:3168
	v_fmac_f32_e32 v94, v102, v39
	v_fmac_f32_e32 v94, v103, v88
	ds_read_b128 v[100:103], v68 offset:5216
	s_waitcnt lgkmcnt(1)
	v_mul_f32_e32 v45, v36, v96
	v_fmac_f32_e32 v45, v46, v32
	v_mul_f32_e32 v46, v36, v97
	s_waitcnt lgkmcnt(0)
	v_fmac_f32_e32 v94, v100, v45
	v_fmac_f32_e32 v46, v47, v33
	v_mul_f32_e32 v47, v36, v98
	v_mul_f32_e32 v89, v36, v99
	v_fmac_f32_e32 v94, v101, v46
	v_fmac_f32_e32 v47, v91, v34
	v_fmac_f32_e32 v89, v92, v35
	ds_read_b128 v[32:35], v68 offset:1136
	ds_read_b128 v[96:99], v68 offset:3184
	v_fmac_f32_e32 v94, v102, v47
	v_fmac_f32_e32 v94, v103, v89
	ds_read_b128 v[100:103], v68 offset:5232
	s_waitcnt lgkmcnt(1)
	v_mul_f32_e32 v90, v36, v96
	v_fmac_f32_e32 v90, v93, v32
	v_mul_f32_e32 v40, v36, v97
	s_waitcnt lgkmcnt(0)
	v_fmac_f32_e32 v94, v100, v90
	v_fmac_f32_e32 v40, v41, v33
	v_mul_f32_e32 v41, v36, v98
	v_fmac_f32_e32 v94, v101, v40
	v_fmac_f32_e32 v41, v42, v34
	v_mul_f32_e32 v36, v36, v99
	v_fmac_f32_e32 v94, v102, v41
	v_fmac_f32_e32 v36, v43, v35
	v_fmac_f32_e32 v94, v103, v36
	ds_write_b32 v86, v94 offset:9216
	ds_read_b128 v[92:95], v68 offset:1536
	ds_read_b128 v[96:99], v68 offset:1552
	ds_read_b128 v[100:103], v68 offset:1568
	ds_read_b128 v[32:35], v68 offset:1584
	ds_read_b128 v[104:107], v68 offset:3584
	ds_read_b128 v[108:111], v68 offset:5632
	s_waitcnt lgkmcnt(1)
	v_mul_f32_e32 v42, v37, v104
	v_mul_f32_e32 v43, v37, v105
	v_fmac_f32_e32 v42, v52, v92
	v_fmac_f32_e32 v43, v53, v93
	v_mul_f32_e32 v52, v37, v106
	v_mul_f32_e32 v53, v37, v107
	v_fmac_f32_e32 v52, v54, v94
	v_fmac_f32_e32 v53, v55, v95
	ds_read_b128 v[92:95], v68 offset:3600
	ds_read_b128 v[104:107], v68 offset:5648
	s_waitcnt lgkmcnt(2)
	v_fma_f32 v91, v108, v42, 0
	v_fmac_f32_e32 v91, v109, v43
	v_fmac_f32_e32 v91, v110, v52
	s_waitcnt lgkmcnt(1)
	v_mul_f32_e32 v55, v37, v93
	v_fmac_f32_e32 v55, v51, v97
	v_mul_f32_e32 v51, v37, v94
	v_mul_f32_e32 v54, v37, v92
	v_fmac_f32_e32 v51, v48, v98
	v_mul_f32_e32 v48, v37, v95
	ds_read_b128 v[92:95], v68 offset:3616
	v_fmac_f32_e32 v91, v111, v53
	v_fmac_f32_e32 v54, v56, v96
	v_fmac_f32_e32 v48, v57, v99
	ds_read_b128 v[96:99], v68 offset:5664
	s_waitcnt lgkmcnt(2)
	v_fmac_f32_e32 v91, v104, v54
	v_fmac_f32_e32 v91, v105, v55
	v_fmac_f32_e32 v91, v106, v51
	s_waitcnt lgkmcnt(1)
	v_mul_f32_e32 v56, v37, v92
	v_fmac_f32_e32 v91, v107, v48
	v_fmac_f32_e32 v56, v58, v100
	v_mul_f32_e32 v57, v37, v93
	s_waitcnt lgkmcnt(0)
	v_fmac_f32_e32 v91, v96, v56
	v_fmac_f32_e32 v57, v59, v101
	v_fmac_f32_e32 v91, v97, v57
	v_mul_f32_e32 v96, v37, v94
	v_mul_f32_e32 v97, v37, v95
	v_fmac_f32_e32 v96, v60, v102
	v_fmac_f32_e32 v97, v61, v103
	ds_read_b128 v[58:61], v68 offset:3632
	ds_read_b128 v[92:95], v68 offset:5680
	v_fmac_f32_e32 v91, v98, v96
	v_fmac_f32_e32 v91, v99, v97
	s_waitcnt lgkmcnt(1)
	v_mul_f32_e32 v98, v37, v58
	v_fmac_f32_e32 v98, v62, v32
	v_mul_f32_e32 v62, v37, v59
	v_fmac_f32_e32 v62, v49, v33
	v_mul_f32_e32 v49, v37, v60
	v_fmac_f32_e32 v49, v50, v34
	v_mul_f32_e32 v50, v37, v61
	s_waitcnt lgkmcnt(0)
	v_fmac_f32_e32 v91, v92, v98
	v_fmac_f32_e32 v50, v63, v35
	ds_read_b128 v[32:35], v68 offset:1600
	ds_read_b128 v[58:61], v68 offset:3648
	v_fmac_f32_e32 v91, v93, v62
	v_fmac_f32_e32 v91, v94, v49
	v_fmac_f32_e32 v91, v95, v50
	ds_read_b128 v[92:95], v68 offset:5696
	s_waitcnt lgkmcnt(1)
	v_mul_f32_e32 v63, v37, v58
	v_fmac_f32_e32 v63, v76, v32
	v_mul_f32_e32 v76, v37, v59
	v_fmac_f32_e32 v76, v78, v33
	v_mul_f32_e32 v78, v37, v60
	v_mul_f32_e32 v99, v37, v61
	s_waitcnt lgkmcnt(0)
	v_fmac_f32_e32 v91, v92, v63
	v_fmac_f32_e32 v78, v44, v34
	v_fmac_f32_e32 v99, v79, v35
	ds_read_b128 v[32:35], v68 offset:1616
	ds_read_b128 v[58:61], v68 offset:3664
	v_fmac_f32_e32 v91, v93, v76
	v_fmac_f32_e32 v91, v94, v78
	v_fmac_f32_e32 v91, v95, v99
	ds_read_b128 v[92:95], v68 offset:5712
	s_waitcnt lgkmcnt(1)
	v_mul_f32_e32 v79, v37, v58
	v_fmac_f32_e32 v79, v87, v32
	v_mul_f32_e32 v87, v37, v59
	v_fmac_f32_e32 v87, v38, v33
	v_mul_f32_e32 v38, v37, v60
	s_waitcnt lgkmcnt(0)
	v_fmac_f32_e32 v91, v92, v79
	v_fmac_f32_e32 v38, v39, v34
	v_mul_f32_e32 v39, v37, v61
	v_fmac_f32_e32 v91, v93, v87
	v_fmac_f32_e32 v39, v88, v35
	ds_read_b128 v[32:35], v68 offset:1632
	ds_read_b128 v[58:61], v68 offset:3680
	v_fmac_f32_e32 v91, v94, v38
	v_fmac_f32_e32 v91, v95, v39
	ds_read_b128 v[92:95], v68 offset:5728
	s_waitcnt lgkmcnt(1)
	v_mul_f32_e32 v88, v37, v58
	v_fmac_f32_e32 v88, v45, v32
	s_waitcnt lgkmcnt(0)
	v_fmac_f32_e32 v91, v92, v88
	v_mul_f32_e32 v92, v37, v59
	v_fmac_f32_e32 v92, v46, v33
	v_fmac_f32_e32 v91, v93, v92
	v_mul_f32_e32 v93, v37, v60
	v_fmac_f32_e32 v93, v47, v34
	v_fmac_f32_e32 v91, v94, v93
	v_mul_f32_e32 v94, v37, v61
	v_fmac_f32_e32 v94, v89, v35
	ds_read_b128 v[32:35], v68 offset:1648
	ds_read_b128 v[44:47], v68 offset:3696
	ds_read_b128 v[58:61], v68 offset:5744
	v_fmac_f32_e32 v91, v95, v94
	s_waitcnt lgkmcnt(1)
	v_mul_f32_e32 v44, v37, v44
	v_mul_f32_e32 v45, v37, v45
	v_fmac_f32_e32 v44, v90, v32
	v_fmac_f32_e32 v45, v40, v33
	v_mul_f32_e32 v40, v37, v46
	v_lshl_add_u64 v[32:33], v[70:71], 0, s[8:9]
	s_waitcnt lgkmcnt(0)
	v_fmac_f32_e32 v91, v58, v44
	v_fmac_f32_e32 v40, v41, v34
	v_mul_f32_e32 v41, v37, v47
	v_add_co_u32_e32 v34, vcc, s13, v32
	v_fmac_f32_e32 v91, v59, v45
	v_fmac_f32_e32 v41, v36, v35
	v_addc_co_u32_e32 v35, vcc, 0, v33, vcc
	v_fmac_f32_e32 v91, v60, v40
	v_add_co_u32_e32 v36, vcc, s70, v32
	v_fmac_f32_e32 v91, v61, v41
	s_nop 0
	v_addc_co_u32_e32 v37, vcc, 0, v33, vcc
	s_movk_i32 s8, 0x3000
	ds_write_b32 v86, v91 offset:9728
	global_store_dword v[32:33], v42, off nt
	global_store_dword v[32:33], v43, off offset:512 nt
	global_store_dword v[32:33], v52, off offset:1024 nt
	global_store_dword v[32:33], v53, off offset:1536 nt
	global_store_dword v[32:33], v54, off offset:2048 nt
	global_store_dword v[32:33], v55, off offset:2560 nt
	global_store_dword v[32:33], v51, off offset:3072 nt
	global_store_dword v[32:33], v48, off offset:3584 nt
	v_add_co_u32_e32 v32, vcc, s8, v32
	global_store_dword v[36:37], v56, off offset:-4096 nt
	global_store_dword v[34:35], v57, off offset:512 nt
	global_store_dword v[34:35], v96, off offset:1024 nt
	global_store_dword v[34:35], v97, off offset:1536 nt
	global_store_dword v[34:35], v98, off offset:2048 nt
	global_store_dword v[34:35], v62, off offset:2560 nt
	global_store_dword v[34:35], v49, off offset:3072 nt
	global_store_dword v[34:35], v50, off offset:3584 nt
	global_store_dword v[36:37], v63, off nt
	global_store_dword v[36:37], v76, off offset:512 nt
	global_store_dword v[36:37], v78, off offset:1024 nt
	global_store_dword v[36:37], v99, off offset:1536 nt
	global_store_dword v[36:37], v79, off offset:2048 nt
	global_store_dword v[36:37], v87, off offset:2560 nt
	global_store_dword v[36:37], v38, off offset:3072 nt
	global_store_dword v[36:37], v39, off offset:3584 nt
	v_addc_co_u32_e32 v33, vcc, 0, v33, vcc
	global_store_dword v[32:33], v88, off nt
	global_store_dword v[32:33], v92, off offset:512 nt
	global_store_dword v[32:33], v93, off offset:1024 nt
	global_store_dword v[32:33], v94, off offset:1536 nt
	global_store_dword v[32:33], v44, off offset:2048 nt
	global_store_dword v[32:33], v45, off offset:2560 nt
	global_store_dword v[32:33], v40, off offset:3072 nt
	global_store_dword v[32:33], v41, off offset:3584 nt
	s_waitcnt lgkmcnt(0)
	s_barrier
	ds_read_b32 v34, v84 offset:8192
	ds_read2st64_b32 v[32:33], v85 offset0:40 offset1:48
	s_waitcnt lgkmcnt(0)
	v_add_f32_e32 v32, v34, v32
	ds_read_b32 v34, v85 offset:14336
	s_waitcnt lgkmcnt(0)
	v_add_f32_e32 v33, v33, v34
	v_add_f32_e32 v32, v32, v33
	v_mul_f32_e32 v33, v32, v32
	s_nop 1
	v_mov_b32_dpp v33, v33 quad_perm:[1,0,3,2] row_mask:0xf bank_mask:0xf
	s_waitcnt lgkmcnt(0)
	v_fmac_f32_e32 v33, v32, v32
	s_nop 1
	v_mov_b32_dpp v34, v33 quad_perm:[2,3,0,1] row_mask:0xf bank_mask:0xf
	s_waitcnt lgkmcnt(0)
	v_add_f32_e32 v33, v33, v34
	s_nop 1
	v_mov_b32_dpp v34, v33 row_half_mirror row_mask:0xf bank_mask:0xf
	s_waitcnt lgkmcnt(0)
	v_add_f32_e32 v33, v33, v34
	s_nop 1
	v_mov_b32_dpp v34, v33 row_ror:8 row_mask:0xf bank_mask:0xf
	s_waitcnt lgkmcnt(0)
	v_add_f32_e32 v33, v33, v34
	v_mov_b32_e32 v34, v33
	s_nop 1
	v_permlane16_swap_b32_e32 v33, v34
	s_waitcnt lgkmcnt(0)
	v_add_f32_e32 v33, v33, v34
	v_mov_b32_e32 v34, v33
	s_nop 1
	v_permlane32_swap_b32_e32 v33, v34
	s_and_saveexec_b64 s[8:9], s[36:37]
	s_cbranch_execz .LBB0_559
	s_waitcnt lgkmcnt(0)
	v_add_f32_e32 v33, v33, v34
	ds_write_b32 v73, v33 offset:16384
	s_branch .LBB0_559

.LBB0_615:
	s_or_b64 exec, exec, s[36:37]
	s_and_b64 vcc, exec, s[56:57]
	s_waitcnt lgkmcnt(0)
	s_barrier
	s_cbranch_vccz .LBB0_617
	s_add_i32 s34, s89, s78
	v_lshl_add_u32 v0, s34, 10, v167
	ds_read_b128 v[0:3], v0 offset:34816
	s_load_dwordx4 s[36:39], s[50:51], 0x78
	s_add_i32 s34, s34, s88
	v_readlane_b32 s72, v253, 10
	s_ashr_i32 s35, s34, 31
	s_waitcnt lgkmcnt(0)
	v_mov_b32_e32 v4, v1
	v_mov_b32_e32 v5, v2
	v_mov_b32_e32 v6, v0
	v_mov_b32_e32 v7, v3
	v_pk_add_f32 v[4:5], v[4:5], v[6:7]
	v_readlane_b32 s73, v253, 11
	v_add_f32_e32 v4, v4, v5
	s_nop 1
	v_mov_b32_dpp v5, v4 quad_perm:[1,0,3,2] row_mask:0xf bank_mask:0xf
	s_lshl_b64 s[34:35], s[34:35], 11
	s_lshl_b64 s[72:73], s[72:73], 2
	s_add_u32 s36, s36, s72
	s_addc_u32 s37, s37, s73
	s_waitcnt lgkmcnt(0)
	v_add_f32_e32 v4, v4, v5
	s_nop 1
	v_mov_b32_dpp v5, v4 quad_perm:[2,3,0,1] row_mask:0xf bank_mask:0xf
	s_waitcnt lgkmcnt(0)
	v_add_f32_e32 v4, v4, v5
	s_nop 1
	v_mov_b32_dpp v5, v4 row_half_mirror row_mask:0xf bank_mask:0xf
	s_waitcnt lgkmcnt(0)
	v_add_f32_e32 v4, v4, v5
	s_nop 1
	v_mov_b32_dpp v5, v4 row_ror:8 row_mask:0xf bank_mask:0xf
	s_waitcnt lgkmcnt(0)
	v_add_f32_e32 v4, v4, v5
	v_mov_b32_e32 v5, v4
	s_nop 1
	v_permlane16_swap_b32_e32 v4, v5
	s_waitcnt lgkmcnt(0)
	v_add_f32_e32 v4, v4, v5
	v_mov_b32_e32 v5, v4
	s_nop 1
	v_permlane32_swap_b32_e32 v4, v5
	s_waitcnt lgkmcnt(0)
	v_add_f32_e32 v4, v4, v5
	v_fmamk_f32 v1, v4, 0xbb800000, v1
	v_fmamk_f32 v0, v4, 0xbb800000, v0
	v_fmamk_f32 v3, v4, 0xbb800000, v3
	v_fmac_f32_e32 v2, 0xbb800000, v4
	v_pk_mul_f32 v[4:5], v[2:3], v[2:3]
	v_pk_mul_f32 v[6:7], v[0:1], v[0:1]
	s_nop 0
	v_pk_mov_b32 v[8:9], v[6:7], v[4:5] op_sel:[1,0]
	v_mov_b32_e32 v7, v5
	v_pk_add_f32 v[4:5], v[8:9], v[6:7]
	global_load_dwordx4 v[6:9], v185, s[36:37]
	s_add_u32 s36, s38, s72
	s_addc_u32 s37, s39, s73
	global_load_dwordx4 v[10:13], v185, s[36:37]
	v_add_f32_e32 v4, v4, v5
	s_nop 1
	v_mov_b32_dpp v5, v4 quad_perm:[1,0,3,2] row_mask:0xf bank_mask:0xf
	s_waitcnt lgkmcnt(0)
	v_add_f32_e32 v4, v4, v5
	s_nop 1
	v_mov_b32_dpp v5, v4 quad_perm:[2,3,0,1] row_mask:0xf bank_mask:0xf
	s_waitcnt lgkmcnt(0)
	v_add_f32_e32 v4, v4, v5
	s_nop 1
	v_mov_b32_dpp v5, v4 row_half_mirror row_mask:0xf bank_mask:0xf
	s_waitcnt lgkmcnt(0)
	v_add_f32_e32 v4, v4, v5
	s_nop 1
	v_mov_b32_dpp v5, v4 row_ror:8 row_mask:0xf bank_mask:0xf
	s_waitcnt lgkmcnt(0)
	v_add_f32_e32 v4, v4, v5
	v_mov_b32_e32 v5, v4
	s_nop 1
	v_permlane16_swap_b32_e32 v4, v5
	s_waitcnt lgkmcnt(0)
	v_add_f32_e32 v4, v4, v5
	v_mov_b32_e32 v5, v4
	s_nop 1
	v_permlane32_swap_b32_e32 v4, v5
	s_waitcnt lgkmcnt(0)
	v_add_f32_e32 v4, v4, v5
	v_fmamk_f32 v4, v4, 0x3b800000, v222
	v_rsq_f32_e32 v4, v4
	s_nop 0
	v_pk_mul_f32 v[0:1], v[0:1], v[4:5] op_sel_hi:[1,0]
	v_pk_mul_f32 v[2:3], v[2:3], v[4:5] op_sel_hi:[1,0]
	s_waitcnt vmcnt(0)
	v_pk_fma_f32 v[0:1], v[6:7], v[0:1], v[10:11]
	s_nop 0
	v_mul_f32_e32 v4, 0xbfb8aa3b, v0
	v_mul_f32_e32 v5, 0xbfb8aa3b, v1
	v_exp_f32_e32 v4, v4
	v_exp_f32_e32 v5, v5
	v_pk_fma_f32 v[2:3], v[8:9], v[2:3], v[12:13]
	v_add_f32_e32 v4, 1.0, v4
	v_add_f32_e32 v5, 1.0, v5
	v_rcp_f32_e32 v4, v4
	v_rcp_f32_e32 v5, v5
	s_nop 0
	v_pk_mul_f32 v[0:1], v[0:1], v[4:5]
	s_nop 0
	v_cvt_pk_bf16_f32 v0, v0, v1
	v_mul_f32_e32 v1, 0xbfb8aa3b, v2
	v_exp_f32_e32 v1, v1
	s_nop 0
	v_add_f32_e32 v1, 1.0, v1
	v_rcp_f32_e32 v4, v1
	v_mul_f32_e32 v1, 0xbfb8aa3b, v3
	v_exp_f32_e32 v1, v1
	s_nop 0
	v_add_f32_e32 v1, 1.0, v1
	v_rcp_f32_e32 v5, v1
	s_nop 0
	v_pk_mul_f32 v[2:3], v[2:3], v[4:5]
	s_nop 0
	v_cvt_pk_bf16_f32 v1, v2, v3
	v_lshl_add_u64 v[2:3], v[132:133], 0, s[34:35]
	global_store_dwordx2 v[2:3], v[0:1], off

.LBB0_620:
	s_or_b32 s37, s85, s89
	s_mul_i32 s34, s37, 0x250
	s_add_i32 s36, s34, 0
	v_lshl_add_u32 v3, v52, 2, s36
	s_waitcnt lgkmcnt(0)
	s_barrier
	ds_read2st64_b32 v[0:1], v3 offset1:1
	v_mov_b32_e32 v2, 0xff800000
	s_and_saveexec_b64 s[34:35], s[20:21]
	ds_read_b32 v2, v3 offset:512
	s_or_b64 exec, exec, s[34:35]
	s_waitcnt lgkmcnt(0)
	v_max3_f32 v3, v0, v1, v2
	s_nop 1
	v_mov_b32_dpp v4, v3 quad_perm:[1,0,3,2] row_mask:0xf bank_mask:0xf
	s_lshl_b32 s34, s37, 8
	s_sub_i32 s36, s36, s34
	s_waitcnt lgkmcnt(0)
	v_max_f32_e32 v4, v4, v4
	v_max_f32_e32 v3, v3, v4
	s_nop 1
	v_mov_b32_dpp v4, v3 quad_perm:[2,3,0,1] row_mask:0xf bank_mask:0xf
	s_waitcnt lgkmcnt(0)
	v_max_f32_e32 v4, v4, v4
	v_max_f32_e32 v3, v3, v4
	s_nop 1
	v_mov_b32_dpp v4, v3 row_half_mirror row_mask:0xf bank_mask:0xf
	s_waitcnt lgkmcnt(0)
	v_max_f32_e32 v4, v4, v4
	v_max_f32_e32 v3, v3, v4
	s_nop 1
	v_mov_b32_dpp v4, v3 row_ror:8 row_mask:0xf bank_mask:0xf
	s_waitcnt lgkmcnt(0)
	v_max_f32_e32 v4, v4, v4
	v_max_f32_e32 v3, v3, v4
	v_mov_b32_e32 v4, v3
	s_nop 1
	v_permlane16_swap_b32_e32 v3, v4
	s_waitcnt lgkmcnt(0)
	v_max_f32_e32 v4, v4, v4
	v_max_f32_e32 v3, v3, v4
	v_mov_b32_e32 v4, v3
	s_nop 1
	v_permlane32_swap_b32_e32 v3, v4
	s_waitcnt lgkmcnt(0)
	v_max3_f32 v3, v3, v4, v141
	v_sub_f32_e32 v0, v0, v3
	v_sub_f32_e32 v1, v1, v3
	v_mul_f32_e32 v0, 0x3fb8aa3b, v0
	v_sub_f32_e32 v2, v2, v3
	v_mul_f32_e32 v1, 0x3fb8aa3b, v1
	v_exp_f32_e32 v4, v0
	v_mul_f32_e32 v2, 0x3fb8aa3b, v2
	v_exp_f32_e32 v5, v1
	v_exp_f32_e32 v0, v2
	v_add_f32_e32 v1, 0, v4
	v_sub_f32_e32 v3, v141, v3
	v_add_f32_e32 v1, v5, v1
	v_add_f32_e32 v1, v0, v1
	s_nop 1
	v_mov_b32_dpp v2, v1 quad_perm:[1,0,3,2] row_mask:0xf bank_mask:0xf
	v_mul_f32_e32 v3, 0x3fb8aa3b, v3
	v_exp_f32_e32 v3, v3
	s_waitcnt lgkmcnt(0)
	v_add_f32_e32 v1, v1, v2
	s_nop 1
	v_mov_b32_dpp v2, v1 quad_perm:[2,3,0,1] row_mask:0xf bank_mask:0xf
	s_waitcnt lgkmcnt(0)
	v_add_f32_e32 v1, v1, v2
	s_nop 1
	v_mov_b32_dpp v2, v1 row_half_mirror row_mask:0xf bank_mask:0xf
	s_waitcnt lgkmcnt(0)
	v_add_f32_e32 v1, v1, v2
	s_nop 1
	v_mov_b32_dpp v2, v1 row_ror:8 row_mask:0xf bank_mask:0xf
	s_waitcnt lgkmcnt(0)
	v_add_f32_e32 v1, v1, v2
	v_mov_b32_e32 v2, v1
	s_nop 1
	v_permlane16_swap_b32_e32 v1, v2
	s_waitcnt lgkmcnt(0)
	v_add_f32_e32 v1, v1, v2
	v_mov_b32_e32 v2, v1
	s_nop 1
	v_permlane32_swap_b32_e32 v1, v2
	s_waitcnt lgkmcnt(0)
	v_add_f32_e32 v1, v1, v2
	v_add_f32_e32 v1, v3, v1
	v_rcp_f32_e32 v1, v1
	v_add_u32_e32 v2, s36, v164
	v_add_u32_e32 v3, s36, v171
	v_mul_f32_e32 v4, v4, v1
	v_mul_f32_e32 v5, v5, v1
	v_cvt_pk_bf16_f32 v4, v4, s0
	v_cvt_pk_bf16_f32 v5, v5, s0
	ds_write_b16 v2, v4 offset:9472
	ds_write_b16 v3, v5 offset:9472
	s_and_saveexec_b64 s[34:35], s[44:45]
	s_movk_i32 s89, 0x1800
	v_mul_f32_e32 v0, v0, v1
	v_add_u32_e32 v2, s36, v172
	v_cvt_pk_bf16_f32 v0, v0, s0
	ds_write_b16 v2, v0 offset:9472
	s_or_b64 exec, exec, s[34:35]
	s_and_b64 vcc, exec, s[62:63]
	s_waitcnt lgkmcnt(0)
	s_barrier
	s_cbranch_vccz .LBB0_569
	ds_read_b128 v[0:3], v187 offset:9472
	ds_read_b128 v[4:7], v188 offset:59648
	ds_read_b128 v[8:11], v187 offset:9536
	ds_read_b128 v[12:15], v187 offset:9600
	ds_read_b128 v[16:19], v187 offset:9728
	s_cmp_eq_u32 s71, 0
	s_waitcnt lgkmcnt(3)
	v_mfma_f32_16x16x32_bf16 v[0:3], v[0:3], v[4:7], 0
	ds_read_b128 v[4:7], v188 offset:59712
	ds_read_b128 v[20:23], v188 offset:59776
	ds_read_b128 v[24:27], v187 offset:9664
	s_cselect_b64 vcc, -1, 0
	s_mov_b32 s71, s55
	s_waitcnt lgkmcnt(2)
	v_mfma_f32_16x16x32_bf16 v[0:3], v[8:11], v[4:7], v[0:3]
	ds_read_b128 v[4:7], v188 offset:59840
	ds_read_b128 v[8:11], v188 offset:59904
	s_waitcnt lgkmcnt(3)
	v_mfma_f32_16x16x32_bf16 v[0:3], v[12:15], v[20:23], v[0:3]
	v_or_b32_e32 v12, s88, v63
	v_ashrrev_i32_e32 v13, 31, v12
	s_waitcnt lgkmcnt(1)
	v_mfma_f32_16x16x32_bf16 v[0:3], v[24:27], v[4:7], v[0:3]
	v_lshlrev_b64 v[4:5], 11, v[12:13]
	v_lshl_add_u64 v[4:5], v[134:135], 0, v[4:5]
	v_lshl_add_u64 v[4:5], v[4:5], 0, s[70:71]
	s_waitcnt lgkmcnt(0)
	v_mfma_f32_16x16x32_bf16 v[0:3], v[16:19], v[8:11], v[0:3]
	s_nop 7
	v_cndmask_b32_e32 v0, v2, v0, vcc
	v_cndmask_b32_e32 v1, v3, v1, vcc
	v_cvt_pk_bf16_f32 v0, v0, s0
	v_cvt_pk_bf16_f32 v1, v1, s0
	global_store_short v[4:5], v0, off
	global_store_short v[4:5], v1, off offset:128
	s_branch .LBB0_569
